# s_setprio 1 while a wave is in its QK phase (VALU-dense), 0 in PV, reset at loop exit
# speedup vs baseline: 1.0986x; 1.0069x over previous
; #define SBAR() __builtin_amdgcn_sched_barrier(0)
; __device__ __forceinline__ unsigned cvtpk(float lo, float hi) { unsigned r; asm volatile("v_cvt_pk_bf16_f32 %0, %1, %2" : "=v"(r) : "v"(lo), "v"(hi)); return r; }
; __device__ __forceinline__ void qkt_fin(f32x16& n0, f32x16& n1, const bf16_t* Ks, const bf16x8* qr, const f32x16& negm, int r32, int hi, ...
;   float psa = 0.f, psb = 0.f; u32x4 wa, wb, wc, wd;
;     ...
; #pragma unroll
;   for (int d0 = 0; d0 < 8; ++d0) { int cb = (d0 * 16 + hi * 8) * 2;
;     bf16x8 b0 = *reinterpret_cast<const bf16x8*>((const char*)Ks + KSWZ(r32, cb));
;     bf16x8 b1 = *reinterpret_cast<const bf16x8*>((const char*)Ks + KSWZ(32 + r32, cb));
;     SBAR(); if (d0 == 0) n0 = __builtin_amdgcn_mfma_f32_32x32x16_bf16(b0, qr[0], negm, 0, 0, 0); else n0 = __builtin_amdgcn_mfma_f32_32x32x16_bf16(b0, qr[d0], n0, 0, 0, 0);
;     SBAR(); QF_CHUNK(2 * d0); SBAR();
;     if (d0 == 0) n1 = __builtin_amdgcn_mfma_f32_32x32x16_bf16(b1, qr[0], negm, 0, 0, 0); else n1 = __builtin_amdgcn_mfma_f32_32x32x16_bf16(b1, qr[d0], n1, 0, 0, 0);
;     SBAR(); QF_CHUNK(2 * d0 + 1); SBAR();
;     if (d0 == 7) { vf8_read<0>(vf0, vbv); SBAR(); } }
;     ...
;   psb += P1[15]; wd[3] = cvtpk(P1[14], P1[15]);
;   l_reg = l_reg * alpha + (psa + psb);
;   pa0 = *reinterpret_cast<bf16x8*>(&wa); pa1 = *reinterpret_cast<bf16x8*>(&wb); pa2 = *reinterpret_cast<bf16x8*>(&wc); pa3 = *reinterpret_cast<bf16x8*>(&wd);
; }
.LBB0_453:
	s_setprio 1
	s_add_i32 s97, s96, 0xffff8000
	s_xor_b32 s98, s96, 0x10000
	s_add_i32 s99, s96, 0x8000
	s_and_b32 s99, s99, 0x18000
	v_add_u32_e32 v196, s96, v236
	ds_read_b128 v[98:101], v196 offset:16384
	ds_read_b128 v[196:199], v196 offset:24576
	v_add_u32_e32 v252, s96, v237
	ds_read_b128 v[248:251], v252 offset:16384
	ds_read_b128 v[252:255], v252 offset:24576
	v_add_u32_e32 v0, s97, v235
	s_waitcnt lgkmcnt(3)
	v_mfma_f32_32x32x16_bf16 v[132:147], v[98:101], v[152:155], v[66:81]
	v_exp_f32_e32 v82, v82
	s_waitcnt lgkmcnt(2)
	v_mfma_f32_32x32x16_bf16 v[98:113], v[196:199], v[152:155], v[66:81]
	v_exp_f32_e32 v83, v83
	v_add_f32_e32 v245, v115, v114
	v_cvt_pk_bf16_f32 v196, v114, v115
	v_add_u32_e32 v206, s96, v238
	ds_read_b128 v[202:205], v206 offset:16384
	ds_read_b128 v[206:209], v206 offset:24576
	s_waitcnt lgkmcnt(3)
	v_mfma_f32_32x32x16_bf16 v[132:147], v[248:251], v[160:163], v[132:147]
	v_exp_f32_e32 v84, v84
	v_add_f32_e32 v245, v116, v245
	v_add_f32_e32 v246, v82, v83
	s_waitcnt lgkmcnt(2)
	v_mfma_f32_32x32x16_bf16 v[98:113], v[252:255], v[160:163], v[98:113]
	v_exp_f32_e32 v85, v85
	v_add_f32_e32 v245, v117, v245
	v_add_f32_e32 v246, v246, v84
	v_cvt_pk_bf16_f32 v197, v116, v117
	v_cvt_pk_bf16_f32 v200, v82, v83
	v_add_u32_e32 v252, s96, v239
	ds_read_b128 v[248:251], v252 offset:16384
	ds_read_b128 v[252:255], v252 offset:24576
	s_waitcnt lgkmcnt(3)
	v_mfma_f32_32x32x16_bf16 v[132:147], v[202:205], v[148:151], v[132:147]
	v_exp_f32_e32 v86, v86
	v_add_f32_e32 v245, v118, v245
	v_add_f32_e32 v246, v246, v85
	s_waitcnt lgkmcnt(2)
	v_mfma_f32_32x32x16_bf16 v[98:113], v[206:209], v[148:151], v[98:113]
	v_exp_f32_e32 v87, v87
	v_add_f32_e32 v245, v119, v245
	v_add_f32_e32 v246, v246, v86
	v_cvt_pk_bf16_f32 v198, v118, v119
	v_cvt_pk_bf16_f32 v201, v84, v85
	v_add_u32_e32 v208, s96, v240
	ds_read_b128 v[204:207], v208 offset:16384
	ds_read_b128 v[208:211], v208 offset:24576
	s_waitcnt lgkmcnt(3)
	v_mfma_f32_32x32x16_bf16 v[132:147], v[248:251], v[156:159], v[132:147]
	v_exp_f32_e32 v88, v88
	v_add_f32_e32 v245, v120, v245
	v_add_f32_e32 v246, v246, v87
	s_waitcnt lgkmcnt(2)
	v_mfma_f32_32x32x16_bf16 v[98:113], v[252:255], v[156:159], v[98:113]
	v_exp_f32_e32 v89, v89
	v_add_f32_e32 v245, v121, v245
	v_add_f32_e32 v246, v246, v88
	v_cvt_pk_bf16_f32 v199, v120, v121
	v_cvt_pk_bf16_f32 v202, v86, v87
	v_add_u32_e32 v252, s96, v241
	ds_read_b128 v[248:251], v252 offset:16384
	ds_read_b128 v[252:255], v252 offset:24576
	s_waitcnt lgkmcnt(3)
	v_mfma_f32_32x32x16_bf16 v[132:147], v[204:207], v[168:171], v[132:147]
	v_exp_f32_e32 v90, v90
	v_add_f32_e32 v245, v122, v245
	v_add_f32_e32 v246, v246, v89
	s_waitcnt lgkmcnt(2)
	v_mfma_f32_32x32x16_bf16 v[98:113], v[208:211], v[168:171], v[98:113]
	v_exp_f32_e32 v91, v91
	v_add_f32_e32 v245, v123, v245
	v_add_f32_e32 v246, v246, v90
	v_cvt_pk_bf16_f32 v204, v122, v123
	v_cvt_pk_bf16_f32 v203, v88, v89
	v_add_u32_e32 v118, s96, v242
	ds_read_b128 v[114:117], v118 offset:16384
	ds_read_b128 v[118:121], v118 offset:24576
	s_waitcnt lgkmcnt(3)
	v_mfma_f32_32x32x16_bf16 v[132:147], v[248:251], v[176:179], v[132:147]
	v_exp_f32_e32 v92, v92
	v_add_f32_e32 v245, v124, v245
	v_add_f32_e32 v246, v246, v91
	s_waitcnt lgkmcnt(2)
	v_mfma_f32_32x32x16_bf16 v[98:113], v[252:255], v[176:179], v[98:113]
	v_exp_f32_e32 v93, v93
	v_add_f32_e32 v245, v125, v245
	v_add_f32_e32 v246, v246, v92
	v_cvt_pk_bf16_f32 v205, v124, v125
	v_cvt_pk_bf16_f32 v208, v90, v91
	v_add_u32_e32 v252, s96, v243
	ds_read_b128 v[248:251], v252 offset:16384
	ds_read_b128 v[252:255], v252 offset:24576
	s_waitcnt lgkmcnt(3)
	v_mfma_f32_32x32x16_bf16 v[132:147], v[114:117], v[164:167], v[132:147]
	v_exp_f32_e32 v94, v94
	v_add_f32_e32 v245, v126, v245
	v_add_f32_e32 v246, v246, v93
	s_waitcnt lgkmcnt(2)
	v_mfma_f32_32x32x16_bf16 v[98:113], v[118:121], v[164:167], v[98:113]
	v_exp_f32_e32 v95, v95
	v_add_f32_e32 v245, v127, v245
	v_add_f32_e32 v246, v246, v94
	v_cvt_pk_bf16_f32 v206, v126, v127
	v_cvt_pk_bf16_f32 v209, v92, v93
	s_waitcnt lgkmcnt(1)
	v_mfma_f32_32x32x16_bf16 v[132:147], v[248:251], v[172:175], v[132:147]
	v_exp_f32_e32 v96, v96
	v_add_f32_e32 v245, v128, v245
	v_add_f32_e32 v246, v246, v95
	s_waitcnt lgkmcnt(0)
	v_mfma_f32_32x32x16_bf16 v[98:113], v[252:255], v[172:175], v[98:113]
	v_exp_f32_e32 v97, v97
	v_add_f32_e32 v245, v129, v245
	v_add_f32_e32 v246, v246, v96
	v_cvt_pk_bf16_f32 v207, v128, v129
	v_cvt_pk_bf16_f32 v210, v94, v95
	v_mov_b32_e32 v131, v97
	v_cvt_pk_bf16_f32 v211, v96, v97
	ds_read_b64_tr_b16 v[94:95], v0 offset:0
	ds_read_b64_tr_b16 v[96:97], v0 offset:2048
	ds_read_b64_tr_b16 v[90:91], v0 offset:4096
	ds_read_b64_tr_b16 v[92:93], v0 offset:6144
	ds_read_b64_tr_b16 v[86:87], v0 offset:8192
	ds_read_b64_tr_b16 v[88:89], v0 offset:10240
	ds_read_b64_tr_b16 v[82:83], v0 offset:12288
	ds_read_b64_tr_b16 v[84:85], v0 offset:14336
	v_cndmask_b32_e64 v114, 0, 1, s[0:1]
	v_cmp_ne_u32_e64 s[8:9], 1, v114
	s_andn2_b64 vcc, exec, s[0:1]
	s_cbranch_vccnz .LBB0_456
; template <bool FIRST, bool DOEXP = true>
; __device__ __forceinline__ void partialSM(f32x16& p0, f32x16& p1, float& m_reg, f32x16& negm, float& alpha, const bool track = true) {
;     ...
;   float pmax = p0[0];
; #pragma unroll
;   for (int r = 1; r < 16; ++r) pmax = fmaxf(pmax, p0[r]);
; #pragma unroll
;   for (int r = 0; r < 16; ++r) pmax = fmaxf(pmax, p1[r]);
;   { auto rr = __builtin_amdgcn_permlane32_swap(__float_as_uint(pmax), __float_as_uint(pmax), false, false);
;     pmax = fmaxf(__uint_as_float(rr[0]), __uint_as_float(rr[1])); }
;   if (!FIRST && __builtin_expect(__all(pmax <= THRL), 1)) { alpha = 1.f; }
;   else { const float dl = FIRST ? pmax : fmaxf(pmax, 0.f); m_reg += dl; alpha = FIRST ? 1.f : __builtin_amdgcn_exp2f(-dl);
; #pragma unroll
;     for (int r = 0; r < 16; ++r) { p0[r] -= dl; p1[r] -= dl; }
; #pragma unroll
;     for (int r = 0; r < 16; ++r) negm[r] = -m_reg;
;     asm volatile("" : "+v"(negm)); }
	v_max_f32_e32 v114, v133, v133
	v_max_f32_e32 v115, v132, v132
	v_max_f32_e32 v114, v115, v114
	v_max3_f32 v114, v114, v134, v135
	v_max3_f32 v114, v114, v136, v137
	v_max3_f32 v114, v114, v138, v139
	v_max3_f32 v114, v114, v140, v141
	v_max3_f32 v114, v114, v142, v143
	v_max3_f32 v114, v114, v144, v145
	v_max3_f32 v114, v114, v146, v147
	v_max3_f32 v114, v114, v98, v99
	v_max3_f32 v114, v114, v100, v101
	v_max3_f32 v114, v114, v102, v103
	v_max3_f32 v114, v114, v104, v105
	v_max3_f32 v114, v114, v106, v107
	v_max3_f32 v114, v114, v108, v109
	v_max3_f32 v114, v114, v110, v111
	v_max3_f32 v114, v114, v112, v113
	v_mov_b32_e32 v115, v114
	s_nop 1
	v_permlane32_swap_b32_e32 v114, v115
	v_max_f32_e32 v115, v115, v115
	v_max_f32_e32 v114, v114, v114
	v_max_f32_e32 v114, v114, v115
	v_cmp_ge_f32_e32 vcc, s69, v114
	s_cmp_eq_u64 vcc, exec
	v_mov_b32_e32 v130, 1.0
	s_cbranch_scc1 .LBB0_457
	v_max_f32_e32 v66, v114, v114
	v_max_f32_e32 v66, 0, v66
	v_exp_f32_e64 v130, -v66
	v_add_f32_e32 v222, v222, v66
	v_sub_f32_e32 v147, v147, v66
	v_sub_f32_e32 v146, v146, v66
	v_sub_f32_e32 v145, v145, v66
	v_sub_f32_e32 v144, v144, v66
	v_sub_f32_e32 v143, v143, v66
	v_sub_f32_e32 v142, v142, v66
	v_sub_f32_e32 v141, v141, v66
	v_sub_f32_e32 v140, v140, v66
	v_sub_f32_e32 v139, v139, v66
	v_sub_f32_e32 v138, v138, v66
	v_sub_f32_e32 v137, v137, v66
	v_sub_f32_e32 v136, v136, v66
	v_sub_f32_e32 v135, v135, v66
	v_sub_f32_e32 v134, v134, v66
	v_sub_f32_e32 v133, v133, v66
	v_sub_f32_e32 v132, v132, v66
	v_sub_f32_e32 v113, v113, v66
	v_sub_f32_e32 v112, v112, v66
	v_sub_f32_e32 v111, v111, v66
	v_sub_f32_e32 v110, v110, v66
	v_sub_f32_e32 v109, v109, v66
	v_sub_f32_e32 v108, v108, v66
	v_sub_f32_e32 v107, v107, v66
	v_sub_f32_e32 v106, v106, v66
	v_sub_f32_e32 v105, v105, v66
	v_sub_f32_e32 v104, v104, v66
	v_sub_f32_e32 v103, v103, v66
	v_sub_f32_e32 v102, v102, v66
	v_sub_f32_e32 v101, v101, v66
	v_sub_f32_e32 v100, v100, v66
	v_sub_f32_e32 v99, v99, v66
	v_sub_f32_e32 v98, v98, v66
	v_xor_b32_e32 v66, 0x80000000, v222
	v_mov_b32_e32 v67, v66
	v_mov_b32_e32 v68, v66
	v_mov_b32_e32 v69, v66
	v_mov_b32_e32 v70, v66
	v_mov_b32_e32 v71, v66
	v_mov_b32_e32 v72, v66
	v_mov_b32_e32 v73, v66
	v_mov_b32_e32 v74, v66
	v_mov_b32_e32 v75, v66
	v_mov_b32_e32 v76, v66
	v_mov_b32_e32 v77, v66
	v_mov_b32_e32 v78, v66
	v_mov_b32_e32 v79, v66
	v_mov_b32_e32 v80, v66
	v_mov_b32_e32 v81, v66
	s_branch .LBB0_457

; #define SBAR() __builtin_amdgcn_sched_barrier(0)
; #define PVE_M(OD, PA, L, H, IDX) do { OD = __builtin_amdgcn_mfma_f32_32x32x16_bf16(PA, PKV(L, H), OD, 0, 0, 0); SBAR(); p[IDX] = __builtin_amdgcn_exp2f(p[IDX]); asm volatile("" : "+v"(p)); SBAR(); } while (0)
; __device__ __forceinline__ void pv_exp(f32x16* o, int vb, bf16x8 pa0, bf16x8 pa1, bf16x8 pa2, bf16x8 pa3, f32x16& p, VF8& fa) {
;   VF8 fb;
;   asm volatile("s_waitcnt lgkmcnt(0)" ::: "memory"); SBAR();
;   PVE_M(o[0], pa0, fa.l0, fa.h0, 0); PVE_M(o[0], pa1, fa.l1, fa.h1, 1); vf8_read<1>(fb, vb); SBAR(); PVE_M(o[0], pa2, fa.l2, fa.h2, 2); PVE_M(o[0], pa3, fa.l3, fa.h3, 3);
;   asm volatile("s_waitcnt lgkmcnt(0)" ::: "memory"); SBAR();
;   PVE_M(o[1], pa0, fb.l0, fb.h0, 4); PVE_M(o[1], pa1, fb.l1, fb.h1, 5); vf8_read<2>(fa, vb); SBAR(); PVE_M(o[1], pa2, fb.l2, fb.h2, 6); PVE_M(o[1], pa3, fb.l3, fb.h3, 7);
;   asm volatile("s_waitcnt lgkmcnt(0)" ::: "memory"); SBAR();
;   PVE_M(o[2], pa0, fa.l0, fa.h0, 8); PVE_M(o[2], pa1, fa.l1, fa.h1, 9); vf8_read<3>(fb, vb); SBAR(); PVE_M(o[2], pa2, fa.l2, fa.h2, 10); PVE_M(o[2], pa3, fa.l3, fa.h3, 11);
;   asm volatile("s_waitcnt lgkmcnt(0)" ::: "memory"); SBAR();
;   PVE_M(o[3], pa0, fb.l0, fb.h0, 12); PVE_M(o[3], pa1, fb.l1, fb.h1, 13); PVE_M(o[3], pa2, fb.l2, fb.h2, 14); PVE_M(o[3], pa3, fb.l3, fb.h3, 15);
; }
.LBB0_457:
	s_setprio 0
	s_waitcnt vmcnt(0)
	s_barrier
	s_waitcnt lgkmcnt(0)
	v_mfma_f32_32x32x16_bf16 v[50:65], v[196:199], v[94:97], v[50:65]
	v_exp_f32_e32 v132, v132
	v_mfma_f32_32x32x16_bf16 v[50:65], v[204:207], v[90:93], v[50:65]
	v_exp_f32_e32 v133, v133
	ds_read_b64_tr_b16 v[90:91], v0 offset:0x200
	ds_read_b64_tr_b16 v[92:93], v0 offset:0xa00
	ds_read_b64_tr_b16 v[94:95], v0 offset:0x1200
	ds_read_b64_tr_b16 v[96:97], v0 offset:0x1a00
	ds_read_b64_tr_b16 v[114:115], v0 offset:0x2200
	ds_read_b64_tr_b16 v[116:117], v0 offset:0x2a00
	ds_read_b64_tr_b16 v[118:119], v0 offset:0x3200
	ds_read_b64_tr_b16 v[120:121], v0 offset:0x3a00
	v_mfma_f32_32x32x16_bf16 v[50:65], v[200:203], v[86:89], v[50:65]
	v_exp_f32_e32 v134, v134
	v_mfma_f32_32x32x16_bf16 v[50:65], v[208:211], v[82:85], v[50:65]
	v_exp_f32_e32 v135, v135
	s_waitcnt lgkmcnt(0)
	v_mfma_f32_32x32x16_bf16 v[34:49], v[196:199], v[90:93], v[34:49]
	v_exp_f32_e32 v136, v136
	s_add_i32 s79, s98, s100
	s_add_i32 m0, s79, 0x4000
	s_add_i32 s79, s79, 0x6000
	global_load_lds_dwordx4 v[180:181], off
	v_mfma_f32_32x32x16_bf16 v[34:49], v[204:207], v[94:97], v[34:49]
	v_exp_f32_e32 v137, v137
	s_mov_b32 m0, s79
	s_add_i32 s79, s98, s101
	global_load_lds_dwordx4 v[182:183], off
	ds_read_b64_tr_b16 v[82:83], v0 offset:0x400
	ds_read_b64_tr_b16 v[84:85], v0 offset:0xc00
	ds_read_b64_tr_b16 v[86:87], v0 offset:0x1400
	ds_read_b64_tr_b16 v[88:89], v0 offset:0x1c00
	ds_read_b64_tr_b16 v[90:91], v0 offset:0x2400
	ds_read_b64_tr_b16 v[92:93], v0 offset:0x2c00
	ds_read_b64_tr_b16 v[94:95], v0 offset:0x3400
	ds_read_b64_tr_b16 v[96:97], v0 offset:0x3c00
	v_mfma_f32_32x32x16_bf16 v[34:49], v[200:203], v[114:117], v[34:49]
	v_exp_f32_e32 v138, v138
	s_mov_b32 m0, s79
	s_add_i32 s79, s79, 0x380
	global_load_lds_dwordx4 v[214:215], off
	v_mfma_f32_32x32x16_bf16 v[34:49], v[208:211], v[118:121], v[34:49]
	v_exp_f32_e32 v139, v139
	s_mov_b32 m0, s79
	s_nop 0
	global_load_lds_dwordx4 v[214:215], off offset:128
	v_lshl_add_u64 v[180:181], v[180:181], 0, s[76:77]
	v_lshl_add_u64 v[182:183], v[182:183], 0, s[76:77]
	v_lshl_add_u64 v[214:215], v[214:215], 0, s[76:77]
	s_waitcnt lgkmcnt(0)
	v_mfma_f32_32x32x16_bf16 v[18:33], v[196:199], v[82:85], v[18:33]
	v_exp_f32_e32 v140, v140
	v_mfma_f32_32x32x16_bf16 v[18:33], v[204:207], v[86:89], v[18:33]
	v_exp_f32_e32 v141, v141
	ds_read_b64_tr_b16 v[82:83], v0 offset:0x600
	ds_read_b64_tr_b16 v[84:85], v0 offset:0xe00
	ds_read_b64_tr_b16 v[86:87], v0 offset:0x1600
	ds_read_b64_tr_b16 v[88:89], v0 offset:0x1e00
	ds_read_b64_tr_b16 v[114:115], v0 offset:0x2600
	ds_read_b64_tr_b16 v[116:117], v0 offset:0x2e00
	ds_read_b64_tr_b16 v[118:119], v0 offset:0x3600
	ds_read_b64_tr_b16 v[120:121], v0 offset:0x3e00
	v_mfma_f32_32x32x16_bf16 v[18:33], v[200:203], v[90:93], v[18:33]
	v_exp_f32_e32 v142, v142
	v_mfma_f32_32x32x16_bf16 v[18:33], v[208:211], v[94:97], v[18:33]
	v_exp_f32_e32 v143, v143
	s_waitcnt lgkmcnt(0)
	v_mfma_f32_32x32x16_bf16 v[2:17], v[196:199], v[82:85], v[2:17]
	v_exp_f32_e32 v144, v144
	v_mfma_f32_32x32x16_bf16 v[2:17], v[204:207], v[86:89], v[2:17]
	v_exp_f32_e32 v145, v145
	v_mfma_f32_32x32x16_bf16 v[2:17], v[200:203], v[114:117], v[2:17]
	v_exp_f32_e32 v146, v146
	v_mfma_f32_32x32x16_bf16 v[2:17], v[208:211], v[118:121], v[2:17]
	v_exp_f32_e32 v147, v147
	v_cmp_gt_f32_e32 vcc, 1.0, v130
	s_cbranch_vccz .LBB0_461
	s_and_saveexec_b64 s[36:37], s[6:7]
	ds_write_b32 v220, v130 offset:128
	s_or_b64 exec, exec, s[36:37]
	s_waitcnt lgkmcnt(0)
	v_add_u32_e32 v94, v213, v212
	ds_read_b128 v[82:85], v94 offset:224
	ds_read_b128 v[86:89], v94 offset:192
	ds_read_b128 v[90:93], v94 offset:160
	ds_read_b128 v[94:97], v94 offset:128
	s_waitcnt lgkmcnt(3)
	v_pk_mul_f32 v[62:63], v[62:63], v[82:83]
	s_waitcnt lgkmcnt(2)
	v_pk_mul_f32 v[58:59], v[58:59], v[86:87]
	s_waitcnt lgkmcnt(1)
	v_pk_mul_f32 v[54:55], v[54:55], v[90:91]
	v_pk_mul_f32 v[64:65], v[64:65], v[84:85]
	v_pk_mul_f32 v[60:61], v[60:61], v[88:89]
	v_pk_mul_f32 v[56:57], v[56:57], v[92:93]
	s_waitcnt lgkmcnt(0)
	v_pk_mul_f32 v[52:53], v[52:53], v[96:97]
	v_pk_mul_f32 v[50:51], v[50:51], v[94:95]
	v_pk_mul_f32 v[46:47], v[46:47], v[82:83]
	v_pk_mul_f32 v[42:43], v[42:43], v[86:87]
	v_pk_mul_f32 v[38:39], v[38:39], v[90:91]
	v_pk_mul_f32 v[48:49], v[48:49], v[84:85]
	v_pk_mul_f32 v[44:45], v[44:45], v[88:89]
	v_pk_mul_f32 v[40:41], v[40:41], v[92:93]
	v_pk_mul_f32 v[36:37], v[36:37], v[96:97]
	v_pk_mul_f32 v[34:35], v[34:35], v[94:95]
	v_pk_mul_f32 v[30:31], v[30:31], v[82:83]
	v_pk_mul_f32 v[26:27], v[26:27], v[86:87]
	v_pk_mul_f32 v[22:23], v[22:23], v[90:91]
	v_pk_mul_f32 v[32:33], v[32:33], v[84:85]
	v_pk_mul_f32 v[28:29], v[28:29], v[88:89]
	v_pk_mul_f32 v[24:25], v[24:25], v[92:93]
	v_pk_mul_f32 v[20:21], v[20:21], v[96:97]
	v_pk_mul_f32 v[18:19], v[18:19], v[94:95]
	v_pk_mul_f32 v[14:15], v[14:15], v[82:83]
	v_pk_mul_f32 v[10:11], v[10:11], v[86:87]
	v_pk_mul_f32 v[6:7], v[6:7], v[90:91]
	v_pk_mul_f32 v[16:17], v[16:17], v[84:85]
	v_pk_mul_f32 v[12:13], v[12:13], v[88:89]
	v_pk_mul_f32 v[8:9], v[8:9], v[92:93]
	v_pk_mul_f32 v[4:5], v[4:5], v[96:97]
	v_pk_mul_f32 v[2:3], v[2:3], v[94:95]
; #define SBAR() __builtin_amdgcn_sched_barrier(0)
; __device__ __forceinline__ unsigned cvtpk(float lo, float hi) { unsigned r; asm volatile("v_cvt_pk_bf16_f32 %0, %1, %2" : "=v"(r) : "v"(lo), "v"(hi)); return r; }
; template <bool FIRST, bool DOEXP = true>
; __device__ __forceinline__ void partialSM(f32x16& p0, f32x16& p1, float& m_reg, f32x16& negm, float& alpha, const bool track = true) {
;     ...
;   float pmax = p0[0];
; #pragma unroll
;   for (int r = 1; r < 16; ++r) pmax = fmaxf(pmax, p0[r]);
; #pragma unroll
;   for (int r = 0; r < 16; ++r) pmax = fmaxf(pmax, p1[r]);
;   { auto rr = __builtin_amdgcn_permlane32_swap(__float_as_uint(pmax), __float_as_uint(pmax), false, false);
;     pmax = fmaxf(__uint_as_float(rr[0]), __uint_as_float(rr[1])); }
;   if (!FIRST && __builtin_expect(__all(pmax <= THRL), 1)) { alpha = 1.f; }
; __device__ __forceinline__ void qkt_fin(f32x16& n0, f32x16& n1, const bf16_t* Ks, const bf16x8* qr, const f32x16& negm, int r32, int hi, ...
;   float psa = 0.f, psb = 0.f; u32x4 wa, wb, wc, wd;
;     ...
; #pragma unroll
;   for (int d0 = 0; d0 < 8; ++d0) { int cb = (d0 * 16 + hi * 8) * 2;
;     bf16x8 b0 = *reinterpret_cast<const bf16x8*>((const char*)Ks + KSWZ(r32, cb));
;     bf16x8 b1 = *reinterpret_cast<const bf16x8*>((const char*)Ks + KSWZ(32 + r32, cb));
;     SBAR(); if (d0 == 0) n0 = __builtin_amdgcn_mfma_f32_32x32x16_bf16(b0, qr[0], negm, 0, 0, 0); else n0 = __builtin_amdgcn_mfma_f32_32x32x16_bf16(b0, qr[d0], n0, 0, 0, 0);
;     SBAR(); QF_CHUNK(2 * d0); SBAR();
;     if (d0 == 0) n1 = __builtin_amdgcn_mfma_f32_32x32x16_bf16(b1, qr[0], negm, 0, 0, 0); else n1 = __builtin_amdgcn_mfma_f32_32x32x16_bf16(b1, qr[d0], n1, 0, 0, 0);
;     SBAR(); QF_CHUNK(2 * d0 + 1); SBAR();
;     if (d0 == 7) { vf8_read<0>(vf0, vbv); SBAR(); } }
;     ...
;   psb += P1[15]; wd[3] = cvtpk(P1[14], P1[15]);
;   l_reg = l_reg * alpha + (psa + psb);
;   pa0 = *reinterpret_cast<bf16x8*>(&wa); pa1 = *reinterpret_cast<bf16x8*>(&wb); pa2 = *reinterpret_cast<bf16x8*>(&wc); pa3 = *reinterpret_cast<bf16x8*>(&wd);
; }
.LBB0_461:
	s_setprio 1
	s_waitcnt lgkmcnt(0)
	v_add_u32_e32 v208, s99, v236
	ds_read_b128 v[204:207], v208 offset:16384
	ds_read_b128 v[208:211], v208 offset:24576
	v_add_u32_e32 v252, s99, v237
	ds_read_b128 v[248:251], v252 offset:16384
	ds_read_b128 v[252:255], v252 offset:24576
	v_add_u32_e32 v203, s96, v235
	s_waitcnt lgkmcnt(3)
	v_mfma_f32_32x32x16_bf16 v[114:129], v[204:207], v[152:155], v[66:81]
	v_exp_f32_e32 v98, v98
	s_waitcnt lgkmcnt(2)
	v_mfma_f32_32x32x16_bf16 v[82:97], v[208:211], v[152:155], v[66:81]
	v_exp_f32_e32 v99, v99
	v_add_f32_e32 v201, v133, v132
	v_cvt_pk_bf16_f32 v132, v132, v133
	v_add_u32_e32 v208, s99, v238
	ds_read_b128 v[204:207], v208 offset:16384
	ds_read_b128 v[208:211], v208 offset:24576
	s_waitcnt lgkmcnt(3)
	v_mfma_f32_32x32x16_bf16 v[114:129], v[248:251], v[160:163], v[114:129]
	v_exp_f32_e32 v100, v100
	v_add_f32_e32 v201, v134, v201
	v_add_f32_e32 v202, v98, v99
	s_waitcnt lgkmcnt(2)
	v_mfma_f32_32x32x16_bf16 v[82:97], v[252:255], v[160:163], v[82:97]
	v_exp_f32_e32 v101, v101
	v_add_f32_e32 v201, v135, v201
	v_add_f32_e32 v202, v202, v100
	v_cvt_pk_bf16_f32 v133, v134, v135
	v_cvt_pk_bf16_f32 v196, v98, v99
	v_add_u32_e32 v252, s99, v239
	ds_read_b128 v[248:251], v252 offset:16384
	ds_read_b128 v[252:255], v252 offset:24576
	s_waitcnt lgkmcnt(3)
	v_mfma_f32_32x32x16_bf16 v[114:129], v[204:207], v[148:151], v[114:129]
	v_exp_f32_e32 v102, v102
	v_add_f32_e32 v201, v136, v201
	v_add_f32_e32 v202, v202, v101
	s_waitcnt lgkmcnt(2)
	v_mfma_f32_32x32x16_bf16 v[82:97], v[208:211], v[148:151], v[82:97]
	v_exp_f32_e32 v103, v103
	v_add_f32_e32 v201, v137, v201
	v_add_f32_e32 v202, v202, v102
	v_cvt_pk_bf16_f32 v134, v136, v137
	v_cvt_pk_bf16_f32 v197, v100, v101
	v_add_u32_e32 v208, s99, v240
	ds_read_b128 v[204:207], v208 offset:16384
	ds_read_b128 v[208:211], v208 offset:24576
	s_waitcnt lgkmcnt(3)
	v_mfma_f32_32x32x16_bf16 v[114:129], v[248:251], v[156:159], v[114:129]
	v_exp_f32_e32 v104, v104
	v_add_f32_e32 v201, v138, v201
	v_add_f32_e32 v202, v202, v103
	s_waitcnt lgkmcnt(2)
	v_mfma_f32_32x32x16_bf16 v[82:97], v[252:255], v[156:159], v[82:97]
	v_exp_f32_e32 v105, v105
	v_add_f32_e32 v201, v139, v201
	v_add_f32_e32 v202, v202, v104
	v_cvt_pk_bf16_f32 v135, v138, v139
	v_cvt_pk_bf16_f32 v198, v102, v103
	v_add_u32_e32 v252, s99, v241
	ds_read_b128 v[248:251], v252 offset:16384
	ds_read_b128 v[252:255], v252 offset:24576
	s_waitcnt lgkmcnt(3)
	v_mfma_f32_32x32x16_bf16 v[114:129], v[204:207], v[168:171], v[114:129]
	v_exp_f32_e32 v106, v106
	v_add_f32_e32 v201, v140, v201
	v_add_f32_e32 v202, v202, v105
	s_waitcnt lgkmcnt(2)
	v_mfma_f32_32x32x16_bf16 v[82:97], v[208:211], v[168:171], v[82:97]
	v_exp_f32_e32 v107, v107
	v_add_f32_e32 v201, v141, v201
	v_add_f32_e32 v202, v202, v106
	v_cvt_pk_bf16_f32 v136, v140, v141
	v_cvt_pk_bf16_f32 v199, v104, v105
	v_add_u32_e32 v208, s99, v242
	ds_read_b128 v[204:207], v208 offset:16384
	ds_read_b128 v[208:211], v208 offset:24576
	s_waitcnt lgkmcnt(3)
	v_mfma_f32_32x32x16_bf16 v[114:129], v[248:251], v[176:179], v[114:129]
	v_exp_f32_e32 v108, v108
	v_add_f32_e32 v201, v142, v201
	v_add_f32_e32 v202, v202, v107
	s_waitcnt lgkmcnt(2)
	v_mfma_f32_32x32x16_bf16 v[82:97], v[252:255], v[176:179], v[82:97]
	v_exp_f32_e32 v109, v109
	v_add_f32_e32 v201, v143, v201
	v_add_f32_e32 v202, v202, v108
	v_cvt_pk_bf16_f32 v137, v142, v143
	v_cvt_pk_bf16_f32 v140, v106, v107
	v_add_u32_e32 v252, s99, v243
	ds_read_b128 v[248:251], v252 offset:16384
	ds_read_b128 v[252:255], v252 offset:24576
	s_waitcnt lgkmcnt(3)
	v_mfma_f32_32x32x16_bf16 v[114:129], v[204:207], v[164:167], v[114:129]
	v_exp_f32_e32 v110, v110
	v_add_f32_e32 v201, v144, v201
	v_add_f32_e32 v202, v202, v109
	s_waitcnt lgkmcnt(2)
	v_mfma_f32_32x32x16_bf16 v[82:97], v[208:211], v[164:167], v[82:97]
	v_exp_f32_e32 v111, v111
	v_add_f32_e32 v201, v145, v201
	v_add_f32_e32 v202, v202, v110
	v_cvt_pk_bf16_f32 v138, v144, v145
	v_cvt_pk_bf16_f32 v141, v108, v109
	s_waitcnt lgkmcnt(1)
	v_mfma_f32_32x32x16_bf16 v[114:129], v[248:251], v[172:175], v[114:129]
	v_exp_f32_e32 v112, v112
	v_add_f32_e32 v201, v146, v201
	v_add_f32_e32 v202, v202, v111
	s_waitcnt lgkmcnt(0)
	v_mfma_f32_32x32x16_bf16 v[82:97], v[252:255], v[172:175], v[82:97]
	v_exp_f32_e32 v113, v113
	v_add_f32_e32 v201, v147, v201
	v_add_f32_e32 v202, v202, v112
	v_cvt_pk_bf16_f32 v139, v146, v147
	v_cvt_pk_bf16_f32 v142, v110, v111
	ds_read_b64_tr_b16 v[144:145], v203 offset:0
	ds_read_b64_tr_b16 v[146:147], v203 offset:2048
	s_nop 0
	ds_read_b64_tr_b16 v[106:107], v203 offset:4096
	ds_read_b64_tr_b16 v[108:109], v203 offset:6144
	ds_read_b64_tr_b16 v[102:103], v203 offset:8192
	ds_read_b64_tr_b16 v[104:105], v203 offset:10240
	ds_read_b64_tr_b16 v[98:99], v203 offset:12288
	ds_read_b64_tr_b16 v[100:101], v203 offset:14336
	v_cvt_pk_bf16_f32 v143, v112, v113
	s_and_b64 vcc, exec, s[8:9]
	v_mov_b32_e32 v200, 1.0
	s_cbranch_vccnz .LBB0_463
	v_max_f32_e32 v110, v115, v115
	v_max_f32_e32 v111, v114, v114
	v_max_f32_e32 v110, v111, v110
	v_max3_f32 v110, v110, v116, v117
	v_max3_f32 v110, v110, v118, v119
	v_max3_f32 v110, v110, v120, v121
	v_max3_f32 v110, v110, v122, v123
	v_max3_f32 v110, v110, v124, v125
	v_max3_f32 v110, v110, v126, v127
	v_max3_f32 v110, v110, v128, v129
	v_max3_f32 v110, v110, v82, v83
	v_max3_f32 v110, v110, v84, v85
	v_max3_f32 v110, v110, v86, v87
	v_max3_f32 v110, v110, v88, v89
	v_max3_f32 v110, v110, v90, v91
	v_max3_f32 v110, v110, v92, v93
	v_max3_f32 v110, v110, v94, v95
	v_max3_f32 v110, v110, v96, v97
	v_mov_b32_e32 v111, v110
	s_nop 1
	v_permlane32_swap_b32_e32 v110, v111
	v_max_f32_e32 v111, v111, v111
	v_max_f32_e32 v110, v110, v110
	v_max_f32_e32 v110, v110, v111
	v_cmp_ge_f32_e32 vcc, s69, v110
	s_cmp_eq_u64 vcc, exec
	v_mov_b32_e32 v200, 1.0
	s_cbranch_scc0 .LBB0_469
; #define SBAR() __builtin_amdgcn_sched_barrier(0)
; #define PVE_M(OD, PA, L, H, IDX) do { OD = __builtin_amdgcn_mfma_f32_32x32x16_bf16(PA, PKV(L, H), OD, 0, 0, 0); SBAR(); p[IDX] = __builtin_amdgcn_exp2f(p[IDX]); asm volatile("" : "+v"(p)); SBAR(); } while (0)
; __device__ __forceinline__ void pv_exp(f32x16* o, int vb, bf16x8 pa0, bf16x8 pa1, bf16x8 pa2, bf16x8 pa3, f32x16& p, VF8& fa) {
;   VF8 fb;
;   asm volatile("s_waitcnt lgkmcnt(0)" ::: "memory"); SBAR();
;   PVE_M(o[0], pa0, fa.l0, fa.h0, 0); PVE_M(o[0], pa1, fa.l1, fa.h1, 1); vf8_read<1>(fb, vb); SBAR(); PVE_M(o[0], pa2, fa.l2, fa.h2, 2); PVE_M(o[0], pa3, fa.l3, fa.h3, 3);
;   asm volatile("s_waitcnt lgkmcnt(0)" ::: "memory"); SBAR();
;   PVE_M(o[1], pa0, fb.l0, fb.h0, 4); PVE_M(o[1], pa1, fb.l1, fb.h1, 5); vf8_read<2>(fa, vb); SBAR(); PVE_M(o[1], pa2, fb.l2, fb.h2, 6); PVE_M(o[1], pa3, fb.l3, fb.h3, 7);
;   asm volatile("s_waitcnt lgkmcnt(0)" ::: "memory"); SBAR();
;   PVE_M(o[2], pa0, fa.l0, fa.h0, 8); PVE_M(o[2], pa1, fa.l1, fa.h1, 9); vf8_read<3>(fb, vb); SBAR(); PVE_M(o[2], pa2, fa.l2, fa.h2, 10); PVE_M(o[2], pa3, fa.l3, fa.h3, 11);
;   asm volatile("s_waitcnt lgkmcnt(0)" ::: "memory"); SBAR();
;   PVE_M(o[3], pa0, fb.l0, fb.h0, 12); PVE_M(o[3], pa1, fb.l1, fb.h1, 13); PVE_M(o[3], pa2, fb.l2, fb.h2, 14); PVE_M(o[3], pa3, fb.l3, fb.h3, 15);
; }
.LBB0_463:
	s_setprio 0
	s_waitcnt vmcnt(0)
	s_barrier
	s_waitcnt lgkmcnt(0)
	v_mfma_f32_32x32x16_bf16 v[50:65], v[132:135], v[144:147], v[50:65]
	v_exp_f32_e32 v114, v114
	v_mfma_f32_32x32x16_bf16 v[50:65], v[136:139], v[106:109], v[50:65]
	v_exp_f32_e32 v115, v115
	ds_read_b64_tr_b16 v[106:107], v203 offset:0x200
	ds_read_b64_tr_b16 v[108:109], v203 offset:0xa00
	ds_read_b64_tr_b16 v[144:145], v203 offset:0x1200
	ds_read_b64_tr_b16 v[146:147], v203 offset:0x1a00
	ds_read_b64_tr_b16 v[204:205], v203 offset:0x2200
	ds_read_b64_tr_b16 v[206:207], v203 offset:0x2a00
	ds_read_b64_tr_b16 v[208:209], v203 offset:0x3200
	ds_read_b64_tr_b16 v[210:211], v203 offset:0x3a00
	v_mfma_f32_32x32x16_bf16 v[50:65], v[196:199], v[102:105], v[50:65]
	v_exp_f32_e32 v116, v116
	v_mfma_f32_32x32x16_bf16 v[50:65], v[140:143], v[98:101], v[50:65]
	v_exp_f32_e32 v117, v117
	s_waitcnt lgkmcnt(0)
	v_mfma_f32_32x32x16_bf16 v[34:49], v[132:135], v[106:109], v[34:49]
	v_exp_f32_e32 v118, v118
	s_add_i32 s79, s97, s100
	s_add_i32 m0, s79, 0x4000
	s_add_i32 s79, s79, 0x6000
	global_load_lds_dwordx4 v[180:181], off
	v_mfma_f32_32x32x16_bf16 v[34:49], v[136:139], v[144:147], v[34:49]
	v_exp_f32_e32 v119, v119
	s_mov_b32 m0, s79
	s_add_i32 s79, s97, s101
	global_load_lds_dwordx4 v[182:183], off
	ds_read_b64_tr_b16 v[98:99], v203 offset:0x400
	ds_read_b64_tr_b16 v[100:101], v203 offset:0xc00
	ds_read_b64_tr_b16 v[102:103], v203 offset:0x1400
	ds_read_b64_tr_b16 v[104:105], v203 offset:0x1c00
	ds_read_b64_tr_b16 v[106:107], v203 offset:0x2400
	ds_read_b64_tr_b16 v[108:109], v203 offset:0x2c00
	ds_read_b64_tr_b16 v[144:145], v203 offset:0x3400
	ds_read_b64_tr_b16 v[146:147], v203 offset:0x3c00
	v_mfma_f32_32x32x16_bf16 v[34:49], v[196:199], v[204:207], v[34:49]
	v_exp_f32_e32 v120, v120
	s_mov_b32 m0, s79
	s_add_i32 s79, s79, 0x380
	global_load_lds_dwordx4 v[214:215], off
	v_mfma_f32_32x32x16_bf16 v[34:49], v[140:143], v[208:211], v[34:49]
	v_exp_f32_e32 v121, v121
	s_mov_b32 m0, s79
	s_nop 0
	global_load_lds_dwordx4 v[214:215], off offset:128
	v_lshl_add_u64 v[180:181], v[180:181], 0, s[76:77]
	v_lshl_add_u64 v[182:183], v[182:183], 0, s[76:77]
	v_lshl_add_u64 v[214:215], v[214:215], 0, s[76:77]
	s_waitcnt lgkmcnt(0)
	v_mfma_f32_32x32x16_bf16 v[18:33], v[132:135], v[98:101], v[18:33]
	v_exp_f32_e32 v122, v122
	v_mfma_f32_32x32x16_bf16 v[18:33], v[136:139], v[102:105], v[18:33]
	v_exp_f32_e32 v123, v123
	ds_read_b64_tr_b16 v[98:99], v203 offset:0x600
	ds_read_b64_tr_b16 v[100:101], v203 offset:0xe00
	ds_read_b64_tr_b16 v[102:103], v203 offset:0x1600
	ds_read_b64_tr_b16 v[104:105], v203 offset:0x1e00
	ds_read_b64_tr_b16 v[204:205], v203 offset:0x2600
	ds_read_b64_tr_b16 v[206:207], v203 offset:0x2e00
	ds_read_b64_tr_b16 v[208:209], v203 offset:0x3600
	ds_read_b64_tr_b16 v[210:211], v203 offset:0x3e00
	v_mfma_f32_32x32x16_bf16 v[18:33], v[196:199], v[106:109], v[18:33]
	v_exp_f32_e32 v124, v124
	v_mfma_f32_32x32x16_bf16 v[18:33], v[140:143], v[144:147], v[18:33]
	v_exp_f32_e32 v125, v125
	s_waitcnt lgkmcnt(0)
	v_mfma_f32_32x32x16_bf16 v[2:17], v[132:135], v[98:101], v[2:17]
	v_exp_f32_e32 v126, v126
	v_mfma_f32_32x32x16_bf16 v[2:17], v[136:139], v[102:105], v[2:17]
	v_exp_f32_e32 v127, v127
	v_mfma_f32_32x32x16_bf16 v[2:17], v[196:199], v[204:207], v[2:17]
	v_exp_f32_e32 v128, v128
	v_mfma_f32_32x32x16_bf16 v[2:17], v[140:143], v[208:211], v[2:17]
	v_exp_f32_e32 v129, v129
	v_cmp_gt_f32_e32 vcc, 1.0, v200
	s_cbranch_vccz .LBB0_467
	s_and_saveexec_b64 s[36:37], s[6:7]
	ds_write_b32 v220, v200 offset:128
	s_or_b64 exec, exec, s[36:37]
	s_waitcnt lgkmcnt(0)
	v_add_u32_e32 v110, v213, v212
	ds_read_b128 v[98:101], v110 offset:224
	ds_read_b128 v[102:105], v110 offset:192
	ds_read_b128 v[106:109], v110 offset:160
	ds_read_b128 v[132:135], v110 offset:128
	s_waitcnt lgkmcnt(3)
	v_pk_mul_f32 v[62:63], v[62:63], v[98:99]
	s_waitcnt lgkmcnt(2)
	v_pk_mul_f32 v[58:59], v[58:59], v[102:103]
	s_waitcnt lgkmcnt(1)
	v_pk_mul_f32 v[54:55], v[54:55], v[106:107]
	v_pk_mul_f32 v[64:65], v[64:65], v[100:101]
	v_pk_mul_f32 v[60:61], v[60:61], v[104:105]
	v_pk_mul_f32 v[56:57], v[56:57], v[108:109]
	s_waitcnt lgkmcnt(0)
	v_pk_mul_f32 v[52:53], v[52:53], v[134:135]
	v_pk_mul_f32 v[50:51], v[50:51], v[132:133]
	v_pk_mul_f32 v[46:47], v[46:47], v[98:99]
	v_pk_mul_f32 v[42:43], v[42:43], v[102:103]
	v_pk_mul_f32 v[38:39], v[38:39], v[106:107]
	v_pk_mul_f32 v[48:49], v[48:49], v[100:101]
	v_pk_mul_f32 v[44:45], v[44:45], v[104:105]
	v_pk_mul_f32 v[40:41], v[40:41], v[108:109]
	v_pk_mul_f32 v[36:37], v[36:37], v[134:135]
	v_pk_mul_f32 v[34:35], v[34:35], v[132:133]
	v_pk_mul_f32 v[30:31], v[30:31], v[98:99]
	v_pk_mul_f32 v[26:27], v[26:27], v[102:103]
	v_pk_mul_f32 v[22:23], v[22:23], v[106:107]
	v_pk_mul_f32 v[32:33], v[32:33], v[100:101]
	v_pk_mul_f32 v[28:29], v[28:29], v[104:105]
	v_pk_mul_f32 v[24:25], v[24:25], v[108:109]
	v_pk_mul_f32 v[20:21], v[20:21], v[134:135]
	v_pk_mul_f32 v[18:19], v[18:19], v[132:133]
	v_pk_mul_f32 v[14:15], v[14:15], v[98:99]
	v_pk_mul_f32 v[10:11], v[10:11], v[102:103]
	v_pk_mul_f32 v[6:7], v[6:7], v[106:107]
	v_pk_mul_f32 v[16:17], v[16:17], v[100:101]
	v_pk_mul_f32 v[12:13], v[12:13], v[104:105]
	v_pk_mul_f32 v[8:9], v[8:9], v[108:109]
	v_pk_mul_f32 v[4:5], v[4:5], v[134:135]
	v_pk_mul_f32 v[2:3], v[2:3], v[132:133]

; #define SBAR() __builtin_amdgcn_sched_barrier(0)
; __device__ __forceinline__ unsigned cvtpk(float lo, float hi) { unsigned r; asm volatile("v_cvt_pk_bf16_f32 %0, %1, %2" : "=v"(r) : "v"(lo), "v"(hi)); return r; }
; __device__ __forceinline__ void qkt_fin(f32x16& n0, f32x16& n1, const bf16_t* Ks, const bf16x8* qr, const f32x16& negm, int r32, int hi, ...
;   float psa = 0.f, psb = 0.f; u32x4 wa, wb, wc, wd;
;     ...
; #pragma unroll
;   for (int d0 = 0; d0 < 8; ++d0) { int cb = (d0 * 16 + hi * 8) * 2;
;     bf16x8 b0 = *reinterpret_cast<const bf16x8*>((const char*)Ks + KSWZ(r32, cb));
;     bf16x8 b1 = *reinterpret_cast<const bf16x8*>((const char*)Ks + KSWZ(32 + r32, cb));
;     SBAR(); if (d0 == 0) n0 = __builtin_amdgcn_mfma_f32_32x32x16_bf16(b0, qr[0], negm, 0, 0, 0); else n0 = __builtin_amdgcn_mfma_f32_32x32x16_bf16(b0, qr[d0], n0, 0, 0, 0);
;     SBAR(); QF_CHUNK(2 * d0); SBAR();
;     if (d0 == 0) n1 = __builtin_amdgcn_mfma_f32_32x32x16_bf16(b1, qr[0], negm, 0, 0, 0); else n1 = __builtin_amdgcn_mfma_f32_32x32x16_bf16(b1, qr[d0], n1, 0, 0, 0);
;     SBAR(); QF_CHUNK(2 * d0 + 1); SBAR();
;     if (d0 == 7) { vf8_read<0>(vf0, vbv); SBAR(); } }
;     ...
;   psb += P1[15]; wd[3] = cvtpk(P1[14], P1[15]);
;   l_reg = l_reg * alpha + (psa + psb);
;   pa0 = *reinterpret_cast<bf16x8*>(&wa); pa1 = *reinterpret_cast<bf16x8*>(&wb); pa2 = *reinterpret_cast<bf16x8*>(&wc); pa3 = *reinterpret_cast<bf16x8*>(&wd);
; }
.Lh2_453:
	s_setprio 1
	s_add_i32 s97, s96, 0xffff8000
	s_xor_b32 s98, s96, 0x10000
	s_add_i32 s99, s96, 0x8000
	s_and_b32 s99, s99, 0x18000
	v_add_u32_e32 v196, s96, v236
	ds_read_b128 v[98:101], v196 offset:16384
	ds_read_b128 v[196:199], v196 offset:24576
	v_add_u32_e32 v252, s96, v237
	ds_read_b128 v[248:251], v252 offset:16384
	ds_read_b128 v[252:255], v252 offset:24576
	v_add_u32_e32 v0, s97, v235
	s_waitcnt lgkmcnt(3)
	v_mfma_f32_32x32x16_bf16 v[132:147], v[98:101], v[152:155], v[66:81]
	v_exp_f32_e32 v82, v82
	s_waitcnt lgkmcnt(2)
	v_mfma_f32_32x32x16_bf16 v[98:113], v[196:199], v[152:155], v[66:81]
	v_exp_f32_e32 v83, v83
	v_add_f32_e32 v245, v115, v114
	v_cvt_pk_bf16_f32 v196, v114, v115
	v_add_u32_e32 v206, s96, v238
	ds_read_b128 v[202:205], v206 offset:16384
	ds_read_b128 v[206:209], v206 offset:24576
	s_waitcnt lgkmcnt(3)
	v_mfma_f32_32x32x16_bf16 v[132:147], v[248:251], v[160:163], v[132:147]
	v_exp_f32_e32 v84, v84
	v_add_f32_e32 v245, v116, v245
	v_add_f32_e32 v246, v82, v83
	s_waitcnt lgkmcnt(2)
	v_mfma_f32_32x32x16_bf16 v[98:113], v[252:255], v[160:163], v[98:113]
	v_exp_f32_e32 v85, v85
	v_add_f32_e32 v245, v117, v245
	v_add_f32_e32 v246, v246, v84
	v_cvt_pk_bf16_f32 v197, v116, v117
	v_cvt_pk_bf16_f32 v200, v82, v83
	v_add_u32_e32 v252, s96, v239
	ds_read_b128 v[248:251], v252 offset:16384
	ds_read_b128 v[252:255], v252 offset:24576
	s_add_i32 s79, s99, s100
	s_add_i32 m0, s79, 0x4000
	s_add_i32 s79, s79, 0x6000
	global_load_lds_dwordx4 v[180:181], off
	s_waitcnt lgkmcnt(3)
	v_mfma_f32_32x32x16_bf16 v[132:147], v[202:205], v[148:151], v[132:147]
	v_exp_f32_e32 v86, v86
	v_add_f32_e32 v245, v118, v245
	v_add_f32_e32 v246, v246, v85
	s_waitcnt lgkmcnt(2)
	v_mfma_f32_32x32x16_bf16 v[98:113], v[206:209], v[148:151], v[98:113]
	v_exp_f32_e32 v87, v87
	v_add_f32_e32 v245, v119, v245
	v_add_f32_e32 v246, v246, v86
	v_cvt_pk_bf16_f32 v198, v118, v119
	v_cvt_pk_bf16_f32 v201, v84, v85
	v_add_u32_e32 v208, s96, v240
	ds_read_b128 v[204:207], v208 offset:16384
	ds_read_b128 v[208:211], v208 offset:24576
	s_mov_b32 m0, s79
	s_add_i32 s79, s99, s101
	global_load_lds_dwordx4 v[182:183], off
	s_waitcnt lgkmcnt(3)
	v_mfma_f32_32x32x16_bf16 v[132:147], v[248:251], v[156:159], v[132:147]
	v_exp_f32_e32 v88, v88
	v_add_f32_e32 v245, v120, v245
	v_add_f32_e32 v246, v246, v87
	s_waitcnt lgkmcnt(2)
	v_mfma_f32_32x32x16_bf16 v[98:113], v[252:255], v[156:159], v[98:113]
	v_exp_f32_e32 v89, v89
	v_add_f32_e32 v245, v121, v245
	v_add_f32_e32 v246, v246, v88
	v_cvt_pk_bf16_f32 v199, v120, v121
	v_cvt_pk_bf16_f32 v202, v86, v87
	v_add_u32_e32 v252, s96, v241
	ds_read_b128 v[248:251], v252 offset:16384
	ds_read_b128 v[252:255], v252 offset:24576
	s_mov_b32 m0, s79
	s_add_i32 s79, s79, 0x380
	global_load_lds_dwordx4 v[214:215], off
	s_waitcnt lgkmcnt(3)
	v_mfma_f32_32x32x16_bf16 v[132:147], v[204:207], v[168:171], v[132:147]
	v_exp_f32_e32 v90, v90
	v_add_f32_e32 v245, v122, v245
	v_add_f32_e32 v246, v246, v89
	s_waitcnt lgkmcnt(2)
	v_mfma_f32_32x32x16_bf16 v[98:113], v[208:211], v[168:171], v[98:113]
	v_exp_f32_e32 v91, v91
	v_add_f32_e32 v245, v123, v245
	v_add_f32_e32 v246, v246, v90
	v_cvt_pk_bf16_f32 v204, v122, v123
	v_cvt_pk_bf16_f32 v203, v88, v89
	v_add_u32_e32 v118, s96, v242
	ds_read_b128 v[114:117], v118 offset:16384
	ds_read_b128 v[118:121], v118 offset:24576
	s_mov_b32 m0, s79
	s_nop 0
	global_load_lds_dwordx4 v[214:215], off offset:128
	v_lshl_add_u64 v[180:181], v[180:181], 0, s[76:77]
	v_lshl_add_u64 v[182:183], v[182:183], 0, s[76:77]
	v_lshl_add_u64 v[214:215], v[214:215], 0, s[76:77]
	s_waitcnt lgkmcnt(3)
	v_mfma_f32_32x32x16_bf16 v[132:147], v[248:251], v[176:179], v[132:147]
	v_exp_f32_e32 v92, v92
	v_add_f32_e32 v245, v124, v245
	v_add_f32_e32 v246, v246, v91
	s_waitcnt lgkmcnt(2)
	v_mfma_f32_32x32x16_bf16 v[98:113], v[252:255], v[176:179], v[98:113]
	v_exp_f32_e32 v93, v93
	v_add_f32_e32 v245, v125, v245
	v_add_f32_e32 v246, v246, v92
	v_cvt_pk_bf16_f32 v205, v124, v125
	v_cvt_pk_bf16_f32 v208, v90, v91
	v_add_u32_e32 v252, s96, v243
	ds_read_b128 v[248:251], v252 offset:16384
	ds_read_b128 v[252:255], v252 offset:24576
	s_waitcnt lgkmcnt(3)
	v_mfma_f32_32x32x16_bf16 v[132:147], v[114:117], v[164:167], v[132:147]
	v_exp_f32_e32 v94, v94
	v_add_f32_e32 v245, v126, v245
	v_add_f32_e32 v246, v246, v93
	s_waitcnt lgkmcnt(2)
	v_mfma_f32_32x32x16_bf16 v[98:113], v[118:121], v[164:167], v[98:113]
	v_exp_f32_e32 v95, v95
	v_add_f32_e32 v245, v127, v245
	v_add_f32_e32 v246, v246, v94
	v_cvt_pk_bf16_f32 v206, v126, v127
	v_cvt_pk_bf16_f32 v209, v92, v93
	s_waitcnt lgkmcnt(1)
	v_mfma_f32_32x32x16_bf16 v[132:147], v[248:251], v[172:175], v[132:147]
	v_exp_f32_e32 v96, v96
	v_add_f32_e32 v245, v128, v245
	v_add_f32_e32 v246, v246, v95
	s_waitcnt lgkmcnt(0)
	v_mfma_f32_32x32x16_bf16 v[98:113], v[252:255], v[172:175], v[98:113]
	v_exp_f32_e32 v97, v97
	v_add_f32_e32 v245, v129, v245
	v_add_f32_e32 v246, v246, v96
	v_cvt_pk_bf16_f32 v207, v128, v129
	v_cvt_pk_bf16_f32 v210, v94, v95
	v_mov_b32_e32 v131, v97
	v_cvt_pk_bf16_f32 v211, v96, v97
	ds_read_b64_tr_b16 v[94:95], v0 offset:0
	ds_read_b64_tr_b16 v[96:97], v0 offset:2048
	ds_read_b64_tr_b16 v[90:91], v0 offset:4096
	ds_read_b64_tr_b16 v[92:93], v0 offset:6144
	ds_read_b64_tr_b16 v[86:87], v0 offset:8192
	ds_read_b64_tr_b16 v[88:89], v0 offset:10240
	ds_read_b64_tr_b16 v[82:83], v0 offset:12288
	ds_read_b64_tr_b16 v[84:85], v0 offset:14336
	v_cndmask_b32_e64 v114, 0, 1, s[0:1]
	v_cmp_ne_u32_e64 s[8:9], 1, v114
	s_andn2_b64 vcc, exec, s[0:1]
	s_cbranch_vccnz .Lh2_456
; template <bool FIRST, bool DOEXP = true>
; __device__ __forceinline__ void partialSM(f32x16& p0, f32x16& p1, float& m_reg, f32x16& negm, float& alpha, const bool track = true) {
;     ...
;   float pmax = p0[0];
; #pragma unroll
;   for (int r = 1; r < 16; ++r) pmax = fmaxf(pmax, p0[r]);
; #pragma unroll
;   for (int r = 0; r < 16; ++r) pmax = fmaxf(pmax, p1[r]);
;   { auto rr = __builtin_amdgcn_permlane32_swap(__float_as_uint(pmax), __float_as_uint(pmax), false, false);
;     pmax = fmaxf(__uint_as_float(rr[0]), __uint_as_float(rr[1])); }
;   if (!FIRST && __builtin_expect(__all(pmax <= THRL), 1)) { alpha = 1.f; }
;   else { const float dl = FIRST ? pmax : fmaxf(pmax, 0.f); m_reg += dl; alpha = FIRST ? 1.f : __builtin_amdgcn_exp2f(-dl);
; #pragma unroll
;     for (int r = 0; r < 16; ++r) { p0[r] -= dl; p1[r] -= dl; }
; #pragma unroll
;     for (int r = 0; r < 16; ++r) negm[r] = -m_reg;
;     asm volatile("" : "+v"(negm)); }
	v_max_f32_e32 v114, v133, v133
	v_max_f32_e32 v115, v132, v132
	v_max_f32_e32 v114, v115, v114
	v_max3_f32 v114, v114, v134, v135
	v_max3_f32 v114, v114, v136, v137
	v_max3_f32 v114, v114, v138, v139
	v_max3_f32 v114, v114, v140, v141
	v_max3_f32 v114, v114, v142, v143
	v_max3_f32 v114, v114, v144, v145
	v_max3_f32 v114, v114, v146, v147
	v_max3_f32 v114, v114, v98, v99
	v_max3_f32 v114, v114, v100, v101
	v_max3_f32 v114, v114, v102, v103
	v_max3_f32 v114, v114, v104, v105
	v_max3_f32 v114, v114, v106, v107
	v_max3_f32 v114, v114, v108, v109
	v_max3_f32 v114, v114, v110, v111
	v_max3_f32 v114, v114, v112, v113
	v_mov_b32_e32 v115, v114
	s_nop 1
	v_permlane32_swap_b32_e32 v114, v115
	v_max_f32_e32 v115, v115, v115
	v_max_f32_e32 v114, v114, v114
	v_max_f32_e32 v114, v114, v115
	v_cmp_ge_f32_e32 vcc, s69, v114
	s_cmp_eq_u64 vcc, exec
	v_mov_b32_e32 v130, 1.0
	s_cbranch_scc1 .Lh2_457
	v_max_f32_e32 v66, v114, v114
	v_max_f32_e32 v66, 0, v66
	v_exp_f32_e64 v130, -v66
	v_add_f32_e32 v222, v222, v66
	v_sub_f32_e32 v147, v147, v66
	v_sub_f32_e32 v146, v146, v66
	v_sub_f32_e32 v145, v145, v66
	v_sub_f32_e32 v144, v144, v66
	v_sub_f32_e32 v143, v143, v66
	v_sub_f32_e32 v142, v142, v66
	v_sub_f32_e32 v141, v141, v66
	v_sub_f32_e32 v140, v140, v66
	v_sub_f32_e32 v139, v139, v66
	v_sub_f32_e32 v138, v138, v66
	v_sub_f32_e32 v137, v137, v66
	v_sub_f32_e32 v136, v136, v66
	v_sub_f32_e32 v135, v135, v66
	v_sub_f32_e32 v134, v134, v66
	v_sub_f32_e32 v133, v133, v66
	v_sub_f32_e32 v132, v132, v66
	v_sub_f32_e32 v113, v113, v66
	v_sub_f32_e32 v112, v112, v66
	v_sub_f32_e32 v111, v111, v66
	v_sub_f32_e32 v110, v110, v66
	v_sub_f32_e32 v109, v109, v66
	v_sub_f32_e32 v108, v108, v66
	v_sub_f32_e32 v107, v107, v66
	v_sub_f32_e32 v106, v106, v66
	v_sub_f32_e32 v105, v105, v66
	v_sub_f32_e32 v104, v104, v66
	v_sub_f32_e32 v103, v103, v66
	v_sub_f32_e32 v102, v102, v66
	v_sub_f32_e32 v101, v101, v66
	v_sub_f32_e32 v100, v100, v66
	v_sub_f32_e32 v99, v99, v66
	v_sub_f32_e32 v98, v98, v66
	v_xor_b32_e32 v66, 0x80000000, v222
	v_mov_b32_e32 v67, v66
	v_mov_b32_e32 v68, v66
	v_mov_b32_e32 v69, v66
	v_mov_b32_e32 v70, v66
	v_mov_b32_e32 v71, v66
	v_mov_b32_e32 v72, v66
	v_mov_b32_e32 v73, v66
	v_mov_b32_e32 v74, v66
	v_mov_b32_e32 v75, v66
	v_mov_b32_e32 v76, v66
	v_mov_b32_e32 v77, v66
	v_mov_b32_e32 v78, v66
	v_mov_b32_e32 v79, v66
	v_mov_b32_e32 v80, v66
	v_mov_b32_e32 v81, v66
	s_branch .Lh2_457

; #define SBAR() __builtin_amdgcn_sched_barrier(0)
; #define PVE_M(OD, PA, L, H, IDX) do { OD = __builtin_amdgcn_mfma_f32_32x32x16_bf16(PA, PKV(L, H), OD, 0, 0, 0); SBAR(); p[IDX] = __builtin_amdgcn_exp2f(p[IDX]); asm volatile("" : "+v"(p)); SBAR(); } while (0)
; __device__ __forceinline__ void pv_exp(f32x16* o, int vb, bf16x8 pa0, bf16x8 pa1, bf16x8 pa2, bf16x8 pa3, f32x16& p, VF8& fa) {
;   VF8 fb;
;   asm volatile("s_waitcnt lgkmcnt(0)" ::: "memory"); SBAR();
;   PVE_M(o[0], pa0, fa.l0, fa.h0, 0); PVE_M(o[0], pa1, fa.l1, fa.h1, 1); vf8_read<1>(fb, vb); SBAR(); PVE_M(o[0], pa2, fa.l2, fa.h2, 2); PVE_M(o[0], pa3, fa.l3, fa.h3, 3);
;   asm volatile("s_waitcnt lgkmcnt(0)" ::: "memory"); SBAR();
;   PVE_M(o[1], pa0, fb.l0, fb.h0, 4); PVE_M(o[1], pa1, fb.l1, fb.h1, 5); vf8_read<2>(fa, vb); SBAR(); PVE_M(o[1], pa2, fb.l2, fb.h2, 6); PVE_M(o[1], pa3, fb.l3, fb.h3, 7);
;   asm volatile("s_waitcnt lgkmcnt(0)" ::: "memory"); SBAR();
;   PVE_M(o[2], pa0, fa.l0, fa.h0, 8); PVE_M(o[2], pa1, fa.l1, fa.h1, 9); vf8_read<3>(fb, vb); SBAR(); PVE_M(o[2], pa2, fa.l2, fa.h2, 10); PVE_M(o[2], pa3, fa.l3, fa.h3, 11);
;   asm volatile("s_waitcnt lgkmcnt(0)" ::: "memory"); SBAR();
;   PVE_M(o[3], pa0, fb.l0, fb.h0, 12); PVE_M(o[3], pa1, fb.l1, fb.h1, 13); PVE_M(o[3], pa2, fb.l2, fb.h2, 14); PVE_M(o[3], pa3, fb.l3, fb.h3, 15);
; }
.Lh2_457:
	s_setprio 0
	s_waitcnt lgkmcnt(0)
	v_mfma_f32_32x32x16_bf16 v[50:65], v[196:199], v[94:97], v[50:65]
	v_exp_f32_e32 v132, v132
	v_mfma_f32_32x32x16_bf16 v[50:65], v[204:207], v[90:93], v[50:65]
	v_exp_f32_e32 v133, v133
	ds_read_b64_tr_b16 v[90:91], v0 offset:0x200
	ds_read_b64_tr_b16 v[92:93], v0 offset:0xa00
	ds_read_b64_tr_b16 v[94:95], v0 offset:0x1200
	ds_read_b64_tr_b16 v[96:97], v0 offset:0x1a00
	ds_read_b64_tr_b16 v[114:115], v0 offset:0x2200
	ds_read_b64_tr_b16 v[116:117], v0 offset:0x2a00
	ds_read_b64_tr_b16 v[118:119], v0 offset:0x3200
	ds_read_b64_tr_b16 v[120:121], v0 offset:0x3a00
	v_mfma_f32_32x32x16_bf16 v[50:65], v[200:203], v[86:89], v[50:65]
	v_exp_f32_e32 v134, v134
	v_mfma_f32_32x32x16_bf16 v[50:65], v[208:211], v[82:85], v[50:65]
	v_exp_f32_e32 v135, v135
	s_waitcnt lgkmcnt(0)
	v_mfma_f32_32x32x16_bf16 v[34:49], v[196:199], v[90:93], v[34:49]
	v_exp_f32_e32 v136, v136
	v_mfma_f32_32x32x16_bf16 v[34:49], v[204:207], v[94:97], v[34:49]
	v_exp_f32_e32 v137, v137
	ds_read_b64_tr_b16 v[82:83], v0 offset:0x400
	ds_read_b64_tr_b16 v[84:85], v0 offset:0xc00
	ds_read_b64_tr_b16 v[86:87], v0 offset:0x1400
	ds_read_b64_tr_b16 v[88:89], v0 offset:0x1c00
	ds_read_b64_tr_b16 v[90:91], v0 offset:0x2400
	ds_read_b64_tr_b16 v[92:93], v0 offset:0x2c00
	ds_read_b64_tr_b16 v[94:95], v0 offset:0x3400
	ds_read_b64_tr_b16 v[96:97], v0 offset:0x3c00
	v_mfma_f32_32x32x16_bf16 v[34:49], v[200:203], v[114:117], v[34:49]
	v_exp_f32_e32 v138, v138
	v_mfma_f32_32x32x16_bf16 v[34:49], v[208:211], v[118:121], v[34:49]
	v_exp_f32_e32 v139, v139
	s_waitcnt lgkmcnt(0)
	v_mfma_f32_32x32x16_bf16 v[18:33], v[196:199], v[82:85], v[18:33]
	v_exp_f32_e32 v140, v140
	v_mfma_f32_32x32x16_bf16 v[18:33], v[204:207], v[86:89], v[18:33]
	v_exp_f32_e32 v141, v141
	ds_read_b64_tr_b16 v[82:83], v0 offset:0x600
	ds_read_b64_tr_b16 v[84:85], v0 offset:0xe00
	ds_read_b64_tr_b16 v[86:87], v0 offset:0x1600
	ds_read_b64_tr_b16 v[88:89], v0 offset:0x1e00
	ds_read_b64_tr_b16 v[114:115], v0 offset:0x2600
	ds_read_b64_tr_b16 v[116:117], v0 offset:0x2e00
	ds_read_b64_tr_b16 v[118:119], v0 offset:0x3600
	ds_read_b64_tr_b16 v[120:121], v0 offset:0x3e00
	v_mfma_f32_32x32x16_bf16 v[18:33], v[200:203], v[90:93], v[18:33]
	v_exp_f32_e32 v142, v142
	v_mfma_f32_32x32x16_bf16 v[18:33], v[208:211], v[94:97], v[18:33]
	v_exp_f32_e32 v143, v143
	s_waitcnt lgkmcnt(0)
	v_mfma_f32_32x32x16_bf16 v[2:17], v[196:199], v[82:85], v[2:17]
	v_exp_f32_e32 v144, v144
	v_mfma_f32_32x32x16_bf16 v[2:17], v[204:207], v[86:89], v[2:17]
	v_exp_f32_e32 v145, v145
	v_mfma_f32_32x32x16_bf16 v[2:17], v[200:203], v[114:117], v[2:17]
	v_exp_f32_e32 v146, v146
	v_mfma_f32_32x32x16_bf16 v[2:17], v[208:211], v[118:121], v[2:17]
	v_exp_f32_e32 v147, v147
	v_cmp_gt_f32_e32 vcc, 1.0, v130
	s_cbranch_vccz .Lh2_461
	s_and_saveexec_b64 s[36:37], s[6:7]
	ds_write_b32 v220, v130 offset:128
	s_or_b64 exec, exec, s[36:37]
	s_waitcnt lgkmcnt(0)
	v_add_u32_e32 v94, v213, v212
	ds_read_b128 v[82:85], v94 offset:224
	ds_read_b128 v[86:89], v94 offset:192
	ds_read_b128 v[90:93], v94 offset:160
	ds_read_b128 v[94:97], v94 offset:128
	s_waitcnt lgkmcnt(3)
	v_pk_mul_f32 v[62:63], v[62:63], v[82:83]
	s_waitcnt lgkmcnt(2)
	v_pk_mul_f32 v[58:59], v[58:59], v[86:87]
	s_waitcnt lgkmcnt(1)
	v_pk_mul_f32 v[54:55], v[54:55], v[90:91]
	v_pk_mul_f32 v[64:65], v[64:65], v[84:85]
	v_pk_mul_f32 v[60:61], v[60:61], v[88:89]
	v_pk_mul_f32 v[56:57], v[56:57], v[92:93]
	s_waitcnt lgkmcnt(0)
	v_pk_mul_f32 v[52:53], v[52:53], v[96:97]
	v_pk_mul_f32 v[50:51], v[50:51], v[94:95]
	v_pk_mul_f32 v[46:47], v[46:47], v[82:83]
	v_pk_mul_f32 v[42:43], v[42:43], v[86:87]
	v_pk_mul_f32 v[38:39], v[38:39], v[90:91]
	v_pk_mul_f32 v[48:49], v[48:49], v[84:85]
	v_pk_mul_f32 v[44:45], v[44:45], v[88:89]
	v_pk_mul_f32 v[40:41], v[40:41], v[92:93]
	v_pk_mul_f32 v[36:37], v[36:37], v[96:97]
	v_pk_mul_f32 v[34:35], v[34:35], v[94:95]
	v_pk_mul_f32 v[30:31], v[30:31], v[82:83]
	v_pk_mul_f32 v[26:27], v[26:27], v[86:87]
	v_pk_mul_f32 v[22:23], v[22:23], v[90:91]
	v_pk_mul_f32 v[32:33], v[32:33], v[84:85]
	v_pk_mul_f32 v[28:29], v[28:29], v[88:89]
	v_pk_mul_f32 v[24:25], v[24:25], v[92:93]
	v_pk_mul_f32 v[20:21], v[20:21], v[96:97]
	v_pk_mul_f32 v[18:19], v[18:19], v[94:95]
	v_pk_mul_f32 v[14:15], v[14:15], v[82:83]
	v_pk_mul_f32 v[10:11], v[10:11], v[86:87]
	v_pk_mul_f32 v[6:7], v[6:7], v[90:91]
	v_pk_mul_f32 v[16:17], v[16:17], v[84:85]
	v_pk_mul_f32 v[12:13], v[12:13], v[88:89]
	v_pk_mul_f32 v[8:9], v[8:9], v[92:93]
	v_pk_mul_f32 v[4:5], v[4:5], v[96:97]
	v_pk_mul_f32 v[2:3], v[2:3], v[94:95]
; #define SBAR() __builtin_amdgcn_sched_barrier(0)
; __device__ __forceinline__ unsigned cvtpk(float lo, float hi) { unsigned r; asm volatile("v_cvt_pk_bf16_f32 %0, %1, %2" : "=v"(r) : "v"(lo), "v"(hi)); return r; }
; template <bool FIRST, bool DOEXP = true>
; __device__ __forceinline__ void partialSM(f32x16& p0, f32x16& p1, float& m_reg, f32x16& negm, float& alpha, const bool track = true) {
;     ...
;   float pmax = p0[0];
; #pragma unroll
;   for (int r = 1; r < 16; ++r) pmax = fmaxf(pmax, p0[r]);
; #pragma unroll
;   for (int r = 0; r < 16; ++r) pmax = fmaxf(pmax, p1[r]);
;   { auto rr = __builtin_amdgcn_permlane32_swap(__float_as_uint(pmax), __float_as_uint(pmax), false, false);
;     pmax = fmaxf(__uint_as_float(rr[0]), __uint_as_float(rr[1])); }
;   if (!FIRST && __builtin_expect(__all(pmax <= THRL), 1)) { alpha = 1.f; }
; __device__ __forceinline__ void qkt_fin(f32x16& n0, f32x16& n1, const bf16_t* Ks, const bf16x8* qr, const f32x16& negm, int r32, int hi, ...
;   float psa = 0.f, psb = 0.f; u32x4 wa, wb, wc, wd;
;     ...
; #pragma unroll
;   for (int d0 = 0; d0 < 8; ++d0) { int cb = (d0 * 16 + hi * 8) * 2;
;     bf16x8 b0 = *reinterpret_cast<const bf16x8*>((const char*)Ks + KSWZ(r32, cb));
;     bf16x8 b1 = *reinterpret_cast<const bf16x8*>((const char*)Ks + KSWZ(32 + r32, cb));
;     SBAR(); if (d0 == 0) n0 = __builtin_amdgcn_mfma_f32_32x32x16_bf16(b0, qr[0], negm, 0, 0, 0); else n0 = __builtin_amdgcn_mfma_f32_32x32x16_bf16(b0, qr[d0], n0, 0, 0, 0);
;     SBAR(); QF_CHUNK(2 * d0); SBAR();
;     if (d0 == 0) n1 = __builtin_amdgcn_mfma_f32_32x32x16_bf16(b1, qr[0], negm, 0, 0, 0); else n1 = __builtin_amdgcn_mfma_f32_32x32x16_bf16(b1, qr[d0], n1, 0, 0, 0);
;     SBAR(); QF_CHUNK(2 * d0 + 1); SBAR();
;     if (d0 == 7) { vf8_read<0>(vf0, vbv); SBAR(); } }
;     ...
;   psb += P1[15]; wd[3] = cvtpk(P1[14], P1[15]);
;   l_reg = l_reg * alpha + (psa + psb);
;   pa0 = *reinterpret_cast<bf16x8*>(&wa); pa1 = *reinterpret_cast<bf16x8*>(&wb); pa2 = *reinterpret_cast<bf16x8*>(&wc); pa3 = *reinterpret_cast<bf16x8*>(&wd);
; }
.Lh2_461:
	s_setprio 1
	s_waitcnt lgkmcnt(0)
	s_waitcnt vmcnt(0)
	s_barrier
	v_add_u32_e32 v208, s99, v236
	ds_read_b128 v[204:207], v208 offset:16384
	ds_read_b128 v[208:211], v208 offset:24576
	v_add_u32_e32 v252, s99, v237
	ds_read_b128 v[248:251], v252 offset:16384
	ds_read_b128 v[252:255], v252 offset:24576
	v_add_u32_e32 v203, s96, v235
	s_waitcnt lgkmcnt(3)
	v_mfma_f32_32x32x16_bf16 v[114:129], v[204:207], v[152:155], v[66:81]
	v_exp_f32_e32 v98, v98
	s_waitcnt lgkmcnt(2)
	v_mfma_f32_32x32x16_bf16 v[82:97], v[208:211], v[152:155], v[66:81]
	v_exp_f32_e32 v99, v99
	v_add_f32_e32 v201, v133, v132
	v_cvt_pk_bf16_f32 v132, v132, v133
	v_add_u32_e32 v208, s99, v238
	ds_read_b128 v[204:207], v208 offset:16384
	ds_read_b128 v[208:211], v208 offset:24576
	s_waitcnt lgkmcnt(3)
	v_mfma_f32_32x32x16_bf16 v[114:129], v[248:251], v[160:163], v[114:129]
	v_exp_f32_e32 v100, v100
	v_add_f32_e32 v201, v134, v201
	v_add_f32_e32 v202, v98, v99
	s_waitcnt lgkmcnt(2)
	v_mfma_f32_32x32x16_bf16 v[82:97], v[252:255], v[160:163], v[82:97]
	v_exp_f32_e32 v101, v101
	v_add_f32_e32 v201, v135, v201
	v_add_f32_e32 v202, v202, v100
	v_cvt_pk_bf16_f32 v133, v134, v135
	v_cvt_pk_bf16_f32 v196, v98, v99
	v_add_u32_e32 v252, s99, v239
	ds_read_b128 v[248:251], v252 offset:16384
	ds_read_b128 v[252:255], v252 offset:24576
	s_add_i32 s79, s98, s100
	s_add_i32 m0, s79, 0x4000
	s_add_i32 s79, s79, 0x6000
	global_load_lds_dwordx4 v[180:181], off
	s_waitcnt lgkmcnt(3)
	v_mfma_f32_32x32x16_bf16 v[114:129], v[204:207], v[148:151], v[114:129]
	v_exp_f32_e32 v102, v102
	v_add_f32_e32 v201, v136, v201
	v_add_f32_e32 v202, v202, v101
	s_waitcnt lgkmcnt(2)
	v_mfma_f32_32x32x16_bf16 v[82:97], v[208:211], v[148:151], v[82:97]
	v_exp_f32_e32 v103, v103
	v_add_f32_e32 v201, v137, v201
	v_add_f32_e32 v202, v202, v102
	v_cvt_pk_bf16_f32 v134, v136, v137
	v_cvt_pk_bf16_f32 v197, v100, v101
	v_add_u32_e32 v208, s99, v240
	ds_read_b128 v[204:207], v208 offset:16384
	ds_read_b128 v[208:211], v208 offset:24576
	s_mov_b32 m0, s79
	s_add_i32 s79, s98, s101
	global_load_lds_dwordx4 v[182:183], off
	s_waitcnt lgkmcnt(3)
	v_mfma_f32_32x32x16_bf16 v[114:129], v[248:251], v[156:159], v[114:129]
	v_exp_f32_e32 v104, v104
	v_add_f32_e32 v201, v138, v201
	v_add_f32_e32 v202, v202, v103
	s_waitcnt lgkmcnt(2)
	v_mfma_f32_32x32x16_bf16 v[82:97], v[252:255], v[156:159], v[82:97]
	v_exp_f32_e32 v105, v105
	v_add_f32_e32 v201, v139, v201
	v_add_f32_e32 v202, v202, v104
	v_cvt_pk_bf16_f32 v135, v138, v139
	v_cvt_pk_bf16_f32 v198, v102, v103
	v_add_u32_e32 v252, s99, v241
	ds_read_b128 v[248:251], v252 offset:16384
	ds_read_b128 v[252:255], v252 offset:24576
	s_mov_b32 m0, s79
	s_add_i32 s79, s79, 0x380
	global_load_lds_dwordx4 v[214:215], off
	s_waitcnt lgkmcnt(3)
	v_mfma_f32_32x32x16_bf16 v[114:129], v[204:207], v[168:171], v[114:129]
	v_exp_f32_e32 v106, v106
	v_add_f32_e32 v201, v140, v201
	v_add_f32_e32 v202, v202, v105
	s_waitcnt lgkmcnt(2)
	v_mfma_f32_32x32x16_bf16 v[82:97], v[208:211], v[168:171], v[82:97]
	v_exp_f32_e32 v107, v107
	v_add_f32_e32 v201, v141, v201
	v_add_f32_e32 v202, v202, v106
	v_cvt_pk_bf16_f32 v136, v140, v141
	v_cvt_pk_bf16_f32 v199, v104, v105
	v_add_u32_e32 v208, s99, v242
	ds_read_b128 v[204:207], v208 offset:16384
	ds_read_b128 v[208:211], v208 offset:24576
	s_mov_b32 m0, s79
	s_nop 0
	global_load_lds_dwordx4 v[214:215], off offset:128
	v_lshl_add_u64 v[180:181], v[180:181], 0, s[76:77]
	v_lshl_add_u64 v[182:183], v[182:183], 0, s[76:77]
	v_lshl_add_u64 v[214:215], v[214:215], 0, s[76:77]
	s_waitcnt lgkmcnt(3)
	v_mfma_f32_32x32x16_bf16 v[114:129], v[248:251], v[176:179], v[114:129]
	v_exp_f32_e32 v108, v108
	v_add_f32_e32 v201, v142, v201
	v_add_f32_e32 v202, v202, v107
	s_waitcnt lgkmcnt(2)
	v_mfma_f32_32x32x16_bf16 v[82:97], v[252:255], v[176:179], v[82:97]
	v_exp_f32_e32 v109, v109
	v_add_f32_e32 v201, v143, v201
	v_add_f32_e32 v202, v202, v108
	v_cvt_pk_bf16_f32 v137, v142, v143
	v_cvt_pk_bf16_f32 v140, v106, v107
	v_add_u32_e32 v252, s99, v243
	ds_read_b128 v[248:251], v252 offset:16384
	ds_read_b128 v[252:255], v252 offset:24576
	s_waitcnt lgkmcnt(3)
	v_mfma_f32_32x32x16_bf16 v[114:129], v[204:207], v[164:167], v[114:129]
	v_exp_f32_e32 v110, v110
	v_add_f32_e32 v201, v144, v201
	v_add_f32_e32 v202, v202, v109
	s_waitcnt lgkmcnt(2)
	v_mfma_f32_32x32x16_bf16 v[82:97], v[208:211], v[164:167], v[82:97]
	v_exp_f32_e32 v111, v111
	v_add_f32_e32 v201, v145, v201
	v_add_f32_e32 v202, v202, v110
	v_cvt_pk_bf16_f32 v138, v144, v145
	v_cvt_pk_bf16_f32 v141, v108, v109
	s_waitcnt lgkmcnt(1)
	v_mfma_f32_32x32x16_bf16 v[114:129], v[248:251], v[172:175], v[114:129]
	v_exp_f32_e32 v112, v112
	v_add_f32_e32 v201, v146, v201
	v_add_f32_e32 v202, v202, v111
	s_waitcnt lgkmcnt(0)
	v_mfma_f32_32x32x16_bf16 v[82:97], v[252:255], v[172:175], v[82:97]
	v_exp_f32_e32 v113, v113
	v_add_f32_e32 v201, v147, v201
	v_add_f32_e32 v202, v202, v112
	v_cvt_pk_bf16_f32 v139, v146, v147
	v_cvt_pk_bf16_f32 v142, v110, v111
	ds_read_b64_tr_b16 v[144:145], v203 offset:0
	ds_read_b64_tr_b16 v[146:147], v203 offset:2048
	s_nop 0
	ds_read_b64_tr_b16 v[106:107], v203 offset:4096
	ds_read_b64_tr_b16 v[108:109], v203 offset:6144
	ds_read_b64_tr_b16 v[102:103], v203 offset:8192
	ds_read_b64_tr_b16 v[104:105], v203 offset:10240
	ds_read_b64_tr_b16 v[98:99], v203 offset:12288
	ds_read_b64_tr_b16 v[100:101], v203 offset:14336
	v_cvt_pk_bf16_f32 v143, v112, v113
	s_and_b64 vcc, exec, s[8:9]
	v_mov_b32_e32 v200, 1.0
	s_cbranch_vccnz .Lh2_463
	v_max_f32_e32 v110, v115, v115
	v_max_f32_e32 v111, v114, v114
	v_max_f32_e32 v110, v111, v110
	v_max3_f32 v110, v110, v116, v117
	v_max3_f32 v110, v110, v118, v119
	v_max3_f32 v110, v110, v120, v121
	v_max3_f32 v110, v110, v122, v123
	v_max3_f32 v110, v110, v124, v125
	v_max3_f32 v110, v110, v126, v127
	v_max3_f32 v110, v110, v128, v129
	v_max3_f32 v110, v110, v82, v83
	v_max3_f32 v110, v110, v84, v85
	v_max3_f32 v110, v110, v86, v87
	v_max3_f32 v110, v110, v88, v89
	v_max3_f32 v110, v110, v90, v91
	v_max3_f32 v110, v110, v92, v93
	v_max3_f32 v110, v110, v94, v95
	v_max3_f32 v110, v110, v96, v97
	v_mov_b32_e32 v111, v110
	s_nop 1
	v_permlane32_swap_b32_e32 v110, v111
	v_max_f32_e32 v111, v111, v111
	v_max_f32_e32 v110, v110, v110
	v_max_f32_e32 v110, v110, v111
	v_cmp_ge_f32_e32 vcc, s69, v110
	s_cmp_eq_u64 vcc, exec
	v_mov_b32_e32 v200, 1.0
	s_cbranch_scc0 .Lh2_469
; #define SBAR() __builtin_amdgcn_sched_barrier(0)
; #define PVE_M(OD, PA, L, H, IDX) do { OD = __builtin_amdgcn_mfma_f32_32x32x16_bf16(PA, PKV(L, H), OD, 0, 0, 0); SBAR(); p[IDX] = __builtin_amdgcn_exp2f(p[IDX]); asm volatile("" : "+v"(p)); SBAR(); } while (0)
; __device__ __forceinline__ void pv_exp(f32x16* o, int vb, bf16x8 pa0, bf16x8 pa1, bf16x8 pa2, bf16x8 pa3, f32x16& p, VF8& fa) {
;   VF8 fb;
;   asm volatile("s_waitcnt lgkmcnt(0)" ::: "memory"); SBAR();
;   PVE_M(o[0], pa0, fa.l0, fa.h0, 0); PVE_M(o[0], pa1, fa.l1, fa.h1, 1); vf8_read<1>(fb, vb); SBAR(); PVE_M(o[0], pa2, fa.l2, fa.h2, 2); PVE_M(o[0], pa3, fa.l3, fa.h3, 3);
;   asm volatile("s_waitcnt lgkmcnt(0)" ::: "memory"); SBAR();
;   PVE_M(o[1], pa0, fb.l0, fb.h0, 4); PVE_M(o[1], pa1, fb.l1, fb.h1, 5); vf8_read<2>(fa, vb); SBAR(); PVE_M(o[1], pa2, fb.l2, fb.h2, 6); PVE_M(o[1], pa3, fb.l3, fb.h3, 7);
;   asm volatile("s_waitcnt lgkmcnt(0)" ::: "memory"); SBAR();
;   PVE_M(o[2], pa0, fa.l0, fa.h0, 8); PVE_M(o[2], pa1, fa.l1, fa.h1, 9); vf8_read<3>(fb, vb); SBAR(); PVE_M(o[2], pa2, fa.l2, fa.h2, 10); PVE_M(o[2], pa3, fa.l3, fa.h3, 11);
;   asm volatile("s_waitcnt lgkmcnt(0)" ::: "memory"); SBAR();
;   PVE_M(o[3], pa0, fb.l0, fb.h0, 12); PVE_M(o[3], pa1, fb.l1, fb.h1, 13); PVE_M(o[3], pa2, fb.l2, fb.h2, 14); PVE_M(o[3], pa3, fb.l3, fb.h3, 15);
; }
.Lh2_463:
	s_setprio 0
	s_waitcnt lgkmcnt(0)
	v_mfma_f32_32x32x16_bf16 v[50:65], v[132:135], v[144:147], v[50:65]
	v_exp_f32_e32 v114, v114
	v_mfma_f32_32x32x16_bf16 v[50:65], v[136:139], v[106:109], v[50:65]
	v_exp_f32_e32 v115, v115
	ds_read_b64_tr_b16 v[106:107], v203 offset:0x200
	ds_read_b64_tr_b16 v[108:109], v203 offset:0xa00
	ds_read_b64_tr_b16 v[144:145], v203 offset:0x1200
	ds_read_b64_tr_b16 v[146:147], v203 offset:0x1a00
	ds_read_b64_tr_b16 v[204:205], v203 offset:0x2200
	ds_read_b64_tr_b16 v[206:207], v203 offset:0x2a00
	ds_read_b64_tr_b16 v[208:209], v203 offset:0x3200
	ds_read_b64_tr_b16 v[210:211], v203 offset:0x3a00
	v_mfma_f32_32x32x16_bf16 v[50:65], v[196:199], v[102:105], v[50:65]
	v_exp_f32_e32 v116, v116
	v_mfma_f32_32x32x16_bf16 v[50:65], v[140:143], v[98:101], v[50:65]
	v_exp_f32_e32 v117, v117
	s_waitcnt lgkmcnt(0)
	v_mfma_f32_32x32x16_bf16 v[34:49], v[132:135], v[106:109], v[34:49]
	v_exp_f32_e32 v118, v118
	v_mfma_f32_32x32x16_bf16 v[34:49], v[136:139], v[144:147], v[34:49]
	v_exp_f32_e32 v119, v119
	ds_read_b64_tr_b16 v[98:99], v203 offset:0x400
	ds_read_b64_tr_b16 v[100:101], v203 offset:0xc00
	ds_read_b64_tr_b16 v[102:103], v203 offset:0x1400
	ds_read_b64_tr_b16 v[104:105], v203 offset:0x1c00
	ds_read_b64_tr_b16 v[106:107], v203 offset:0x2400
	ds_read_b64_tr_b16 v[108:109], v203 offset:0x2c00
	ds_read_b64_tr_b16 v[144:145], v203 offset:0x3400
	ds_read_b64_tr_b16 v[146:147], v203 offset:0x3c00
	v_mfma_f32_32x32x16_bf16 v[34:49], v[196:199], v[204:207], v[34:49]
	v_exp_f32_e32 v120, v120
	v_mfma_f32_32x32x16_bf16 v[34:49], v[140:143], v[208:211], v[34:49]
	v_exp_f32_e32 v121, v121
	s_waitcnt lgkmcnt(0)
	v_mfma_f32_32x32x16_bf16 v[18:33], v[132:135], v[98:101], v[18:33]
	v_exp_f32_e32 v122, v122
	v_mfma_f32_32x32x16_bf16 v[18:33], v[136:139], v[102:105], v[18:33]
	v_exp_f32_e32 v123, v123
	ds_read_b64_tr_b16 v[98:99], v203 offset:0x600
	ds_read_b64_tr_b16 v[100:101], v203 offset:0xe00
	ds_read_b64_tr_b16 v[102:103], v203 offset:0x1600
	ds_read_b64_tr_b16 v[104:105], v203 offset:0x1e00
	ds_read_b64_tr_b16 v[204:205], v203 offset:0x2600
	ds_read_b64_tr_b16 v[206:207], v203 offset:0x2e00
	ds_read_b64_tr_b16 v[208:209], v203 offset:0x3600
	ds_read_b64_tr_b16 v[210:211], v203 offset:0x3e00
	v_mfma_f32_32x32x16_bf16 v[18:33], v[196:199], v[106:109], v[18:33]
	v_exp_f32_e32 v124, v124
	v_mfma_f32_32x32x16_bf16 v[18:33], v[140:143], v[144:147], v[18:33]
	v_exp_f32_e32 v125, v125
	s_waitcnt lgkmcnt(0)
	v_mfma_f32_32x32x16_bf16 v[2:17], v[132:135], v[98:101], v[2:17]
	v_exp_f32_e32 v126, v126
	v_mfma_f32_32x32x16_bf16 v[2:17], v[136:139], v[102:105], v[2:17]
	v_exp_f32_e32 v127, v127
	v_mfma_f32_32x32x16_bf16 v[2:17], v[196:199], v[204:207], v[2:17]
	v_exp_f32_e32 v128, v128
	v_mfma_f32_32x32x16_bf16 v[2:17], v[140:143], v[208:211], v[2:17]
	v_exp_f32_e32 v129, v129
	v_cmp_gt_f32_e32 vcc, 1.0, v200
	s_cbranch_vccz .Lh2_467
	s_and_saveexec_b64 s[36:37], s[6:7]
	ds_write_b32 v220, v200 offset:128
	s_or_b64 exec, exec, s[36:37]
	s_waitcnt lgkmcnt(0)
	v_add_u32_e32 v110, v213, v212
	ds_read_b128 v[98:101], v110 offset:224
	ds_read_b128 v[102:105], v110 offset:192
	ds_read_b128 v[106:109], v110 offset:160
	ds_read_b128 v[132:135], v110 offset:128
	s_waitcnt lgkmcnt(3)
	v_pk_mul_f32 v[62:63], v[62:63], v[98:99]
	s_waitcnt lgkmcnt(2)
	v_pk_mul_f32 v[58:59], v[58:59], v[102:103]
	s_waitcnt lgkmcnt(1)
	v_pk_mul_f32 v[54:55], v[54:55], v[106:107]
	v_pk_mul_f32 v[64:65], v[64:65], v[100:101]
	v_pk_mul_f32 v[60:61], v[60:61], v[104:105]
	v_pk_mul_f32 v[56:57], v[56:57], v[108:109]
	s_waitcnt lgkmcnt(0)
	v_pk_mul_f32 v[52:53], v[52:53], v[134:135]
	v_pk_mul_f32 v[50:51], v[50:51], v[132:133]
	v_pk_mul_f32 v[46:47], v[46:47], v[98:99]
	v_pk_mul_f32 v[42:43], v[42:43], v[102:103]
	v_pk_mul_f32 v[38:39], v[38:39], v[106:107]
	v_pk_mul_f32 v[48:49], v[48:49], v[100:101]
	v_pk_mul_f32 v[44:45], v[44:45], v[104:105]
	v_pk_mul_f32 v[40:41], v[40:41], v[108:109]
	v_pk_mul_f32 v[36:37], v[36:37], v[134:135]
	v_pk_mul_f32 v[34:35], v[34:35], v[132:133]
	v_pk_mul_f32 v[30:31], v[30:31], v[98:99]
	v_pk_mul_f32 v[26:27], v[26:27], v[102:103]
	v_pk_mul_f32 v[22:23], v[22:23], v[106:107]
	v_pk_mul_f32 v[32:33], v[32:33], v[100:101]
	v_pk_mul_f32 v[28:29], v[28:29], v[104:105]
	v_pk_mul_f32 v[24:25], v[24:25], v[108:109]
	v_pk_mul_f32 v[20:21], v[20:21], v[134:135]
	v_pk_mul_f32 v[18:19], v[18:19], v[132:133]
	v_pk_mul_f32 v[14:15], v[14:15], v[98:99]
	v_pk_mul_f32 v[10:11], v[10:11], v[102:103]
	v_pk_mul_f32 v[6:7], v[6:7], v[106:107]
	v_pk_mul_f32 v[16:17], v[16:17], v[100:101]
	v_pk_mul_f32 v[12:13], v[12:13], v[104:105]
	v_pk_mul_f32 v[8:9], v[8:9], v[108:109]
	v_pk_mul_f32 v[4:5], v[4:5], v[134:135]
	v_pk_mul_f32 v[2:3], v[2:3], v[132:133]

; #define SBAR() __builtin_amdgcn_sched_barrier(0)
; __device__ __forceinline__ unsigned cvtpk(float lo, float hi) { unsigned r; asm volatile("v_cvt_pk_bf16_f32 %0, %1, %2" : "=v"(r) : "v"(lo), "v"(hi)); return r; }
; __device__ __forceinline__ void qkt_fin(f32x16& n0, f32x16& n1, const bf16_t* Ks, const bf16x8* qr, const f32x16& negm, int r32, int hi, ...
;   float psa = 0.f, psb = 0.f; u32x4 wa, wb, wc, wd;
;     ...
; #pragma unroll
;   for (int d0 = 0; d0 < 8; ++d0) { int cb = (d0 * 16 + hi * 8) * 2;
;     bf16x8 b0 = *reinterpret_cast<const bf16x8*>((const char*)Ks + KSWZ(r32, cb));
;     bf16x8 b1 = *reinterpret_cast<const bf16x8*>((const char*)Ks + KSWZ(32 + r32, cb));
;     SBAR(); if (d0 == 0) n0 = __builtin_amdgcn_mfma_f32_32x32x16_bf16(b0, qr[0], negm, 0, 0, 0); else n0 = __builtin_amdgcn_mfma_f32_32x32x16_bf16(b0, qr[d0], n0, 0, 0, 0);
;     SBAR(); QF_CHUNK(2 * d0); SBAR();
;     if (d0 == 0) n1 = __builtin_amdgcn_mfma_f32_32x32x16_bf16(b1, qr[0], negm, 0, 0, 0); else n1 = __builtin_amdgcn_mfma_f32_32x32x16_bf16(b1, qr[d0], n1, 0, 0, 0);
;     SBAR(); QF_CHUNK(2 * d0 + 1); SBAR();
;     if (d0 == 7) { vf8_read<0>(vf0, vbv); SBAR(); } }
;     ...
;   psb += P1[15]; wd[3] = cvtpk(P1[14], P1[15]);
;   l_reg = l_reg * alpha + (psa + psb);
;   pa0 = *reinterpret_cast<bf16x8*>(&wa); pa1 = *reinterpret_cast<bf16x8*>(&wb); pa2 = *reinterpret_cast<bf16x8*>(&wc); pa3 = *reinterpret_cast<bf16x8*>(&wd);
; }
; __device__ __forceinline__ void attn_item(const bf16_t* __restrict__ Qb, const bf16_t* __restrict__ Kh, const bf16_t* __restrict__ Vh, const bf16_t* __restrict__ Zb, ...
;     ...
;   SBAR(); qkt_fin(pB0, pB1, (const bf16_t*)(lds + s_cur + KOFF), qr, negm, r32, hi, pA0, pA1, alA, l_reg, pa0, pa1, pa2, pa3, vfa, vb0 + s_prev); SBAR();
;   partialSM<false, false>(pB0, pB1, m_reg, negm, alB, track); SBAR(); pv_exp(o, vb0 + s_prev, pa0, pa1, pa2, pa3, pB0, vfa);
.LBB0_470:
	s_setprio 0
	s_waitcnt vmcnt(0)
	s_mov_b32 s80, 0x18000
	s_mov_b32 s76, 0x10000
	v_add_u32_e32 v0, 0x18000, v235
	v_add3_u32 v98, s80, v234, v221
	ds_read_b128 v[130:133], v98 offset:16384
	ds_read_b128 v[134:137], v98 offset:24576
	v_add_u32_e32 v180, s76, v235
	s_waitcnt lgkmcnt(1)
	v_mfma_f32_32x32x16_bf16 v[98:113], v[130:133], v[152:155], v[66:81]
	v_exp_f32_e32 v82, v82
	v_add_f32_e32 v130, 0, v114
	v_mov_b32_e32 v131, v1
	s_waitcnt lgkmcnt(0)
	v_mfma_f32_32x32x16_bf16 v[66:81], v[134:137], v[152:155], v[66:81]
	v_exp_f32_e32 v83, v83
	v_add_f32_e32 v140, v115, v130
	v_add_f32_e32 v131, v131, v82
	v_cvt_pk_bf16_f32 v130, v114, v115
	v_add3_u32 v114, s80, v233, v221
	ds_read_b128 v[132:135], v114 offset:16384
	ds_read_b128 v[136:139], v114 offset:24576
	s_waitcnt lgkmcnt(1)
	v_mfma_f32_32x32x16_bf16 v[98:113], v[132:135], v[160:163], v[98:113]
	v_exp_f32_e32 v84, v84
	v_add_f32_e32 v114, v116, v140
	v_add_f32_e32 v115, v131, v83
	s_waitcnt lgkmcnt(0)
	v_mfma_f32_32x32x16_bf16 v[66:81], v[136:139], v[160:163], v[66:81]
	v_exp_f32_e32 v85, v85
	v_add_f32_e32 v132, v117, v114
	v_add_f32_e32 v133, v115, v84
	v_cvt_pk_bf16_f32 v131, v116, v117
	v_cvt_pk_bf16_f32 v134, v82, v83
	v_add3_u32 v135, s80, v230, v221
	ds_read_b128 v[114:117], v135 offset:16384
	ds_read_b128 v[136:139], v135 offset:24576
	s_waitcnt lgkmcnt(1)
	v_mfma_f32_32x32x16_bf16 v[98:113], v[114:117], v[148:151], v[98:113]
	v_exp_f32_e32 v86, v86
	v_add_f32_e32 v114, v118, v132
	v_add_f32_e32 v115, v133, v85
	s_waitcnt lgkmcnt(0)
	v_mfma_f32_32x32x16_bf16 v[66:81], v[136:139], v[148:151], v[66:81]
	v_exp_f32_e32 v87, v87
	v_add_f32_e32 v133, v119, v114
	v_add_f32_e32 v140, v115, v86
	v_cvt_pk_bf16_f32 v132, v118, v119
	v_cvt_pk_bf16_f32 v135, v84, v85
	v_add3_u32 v118, s80, v227, v221
	ds_read_b128 v[114:117], v118 offset:16384
	ds_read_b128 v[136:139], v118 offset:24576
	s_waitcnt lgkmcnt(1)
	v_mfma_f32_32x32x16_bf16 v[98:113], v[114:117], v[156:159], v[98:113]
	v_exp_f32_e32 v88, v88
	v_add_f32_e32 v114, v120, v133
	v_add_f32_e32 v115, v140, v87
	s_waitcnt lgkmcnt(0)
	v_mfma_f32_32x32x16_bf16 v[66:81], v[136:139], v[156:159], v[66:81]
	v_exp_f32_e32 v89, v89
	v_add_f32_e32 v137, v121, v114
	v_add_f32_e32 v138, v115, v88
	v_cvt_pk_bf16_f32 v133, v120, v121
	v_cvt_pk_bf16_f32 v136, v86, v87
	v_add3_u32 v118, s80, v226, v221
	ds_read_b128 v[114:117], v118 offset:16384
	ds_read_b128 v[118:121], v118 offset:24576
	s_waitcnt lgkmcnt(1)
	v_mfma_f32_32x32x16_bf16 v[98:113], v[114:117], v[168:171], v[98:113]
	v_exp_f32_e32 v90, v90
	v_add_f32_e32 v114, v122, v137
	v_add_f32_e32 v115, v138, v89
	s_waitcnt lgkmcnt(0)
	v_mfma_f32_32x32x16_bf16 v[66:81], v[118:121], v[168:171], v[66:81]
	v_exp_f32_e32 v91, v91
	v_add_f32_e32 v139, v123, v114
	v_add_f32_e32 v140, v115, v90
	v_cvt_pk_bf16_f32 v138, v122, v123
	v_cvt_pk_bf16_f32 v137, v88, v89
	v_add3_u32 v118, s80, v225, v221
	ds_read_b128 v[114:117], v118 offset:16384
	ds_read_b128 v[118:121], v118 offset:24576
	s_waitcnt lgkmcnt(1)
	v_mfma_f32_32x32x16_bf16 v[98:113], v[114:117], v[176:179], v[98:113]
	v_exp_f32_e32 v92, v92
	v_add_f32_e32 v114, v124, v139
	v_add_f32_e32 v115, v140, v91
	s_waitcnt lgkmcnt(0)
	v_mfma_f32_32x32x16_bf16 v[66:81], v[118:121], v[176:179], v[66:81]
	v_exp_f32_e32 v93, v93
	v_add_f32_e32 v122, v125, v114
	v_add_f32_e32 v123, v115, v92
	v_cvt_pk_bf16_f32 v139, v124, v125
	v_cvt_pk_bf16_f32 v142, v90, v91
	v_add3_u32 v118, s80, v224, v221
	ds_read_b128 v[114:117], v118 offset:16384
	ds_read_b128 v[118:121], v118 offset:24576
	s_waitcnt lgkmcnt(1)
	v_mfma_f32_32x32x16_bf16 v[98:113], v[114:117], v[164:167], v[98:113]
	v_exp_f32_e32 v94, v94
	v_add_f32_e32 v114, v126, v122
	v_add_f32_e32 v115, v123, v93
	s_waitcnt lgkmcnt(0)
	v_mfma_f32_32x32x16_bf16 v[66:81], v[118:121], v[164:167], v[66:81]
	v_exp_f32_e32 v95, v95
	v_add_f32_e32 v122, v127, v114
	v_add_f32_e32 v123, v115, v94
	v_cvt_pk_bf16_f32 v140, v126, v127
	v_cvt_pk_bf16_f32 v143, v92, v93
	v_add3_u32 v118, s80, v223, v221
	ds_read_b128 v[114:117], v118 offset:16384
	ds_read_b128 v[118:121], v118 offset:24576
	s_waitcnt lgkmcnt(1)
	v_mfma_f32_32x32x16_bf16 v[98:113], v[114:117], v[172:175], v[98:113]
	v_exp_f32_e32 v96, v96
	v_add_f32_e32 v114, v128, v122
	v_add_f32_e32 v115, v123, v95
	s_waitcnt lgkmcnt(0)
	v_mfma_f32_32x32x16_bf16 v[66:81], v[118:121], v[172:175], v[66:81]
	v_exp_f32_e32 v97, v97
	v_add_f32_e32 v150, v129, v114
	v_add_f32_e32 v151, v115, v96
	v_cvt_pk_bf16_f32 v141, v128, v129
	v_cvt_pk_bf16_f32 v144, v94, v95
	ds_read_b64_tr_b16 v[146:147], v180 offset:0
	ds_read_b64_tr_b16 v[148:149], v180 offset:0x800
	s_nop 0
	ds_read_b64_tr_b16 v[90:91], v180 offset:0x1000
	ds_read_b64_tr_b16 v[92:93], v180 offset:0x1800
	ds_read_b64_tr_b16 v[86:87], v180 offset:0x2000
	ds_read_b64_tr_b16 v[88:89], v180 offset:0x2800
	ds_read_b64_tr_b16 v[82:83], v180 offset:0x3000
	ds_read_b64_tr_b16 v[84:85], v180 offset:0x3800
	v_cvt_pk_bf16_f32 v145, v96, v97
	s_and_b64 vcc, exec, s[8:9]
	v_mov_b32_e32 v94, 1.0
	s_cbranch_vccnz .LBB0_472
	v_max_f32_e32 v94, v99, v99
	v_max_f32_e32 v95, v98, v98
	v_max_f32_e32 v94, v95, v94
	v_max3_f32 v94, v94, v100, v101
	v_max3_f32 v94, v94, v102, v103
	v_max3_f32 v94, v94, v104, v105
	v_max3_f32 v94, v94, v106, v107
	v_max3_f32 v94, v94, v108, v109
	v_max3_f32 v94, v94, v110, v111
	v_max3_f32 v94, v94, v112, v113
	v_max3_f32 v94, v94, v66, v67
	v_max3_f32 v94, v94, v68, v69
	v_max3_f32 v94, v94, v70, v71
	v_max3_f32 v94, v94, v72, v73
	v_max3_f32 v94, v94, v74, v75
	v_max3_f32 v94, v94, v76, v77
	v_max3_f32 v94, v94, v78, v79
	v_max3_f32 v94, v94, v80, v81
	v_mov_b32_e32 v95, v94
	s_nop 1
	v_permlane32_swap_b32_e32 v94, v95
	v_max_f32_e32 v95, v95, v95
	v_max_f32_e32 v94, v94, v94
	v_max_f32_e32 v95, v94, v95
	v_cmp_ge_f32_e32 vcc, s69, v95
	s_cmp_eq_u64 vcc, exec
	v_mov_b32_e32 v94, 1.0
	s_cbranch_scc0 .LBB0_478
